# P7 upconv epilogue rewritten by hand: conv taps via v_fmac_f32_dpp row_shr/row_shl, all loads issued up front, 1070 vs 1937 instr per wave
# speedup vs baseline: 1.0092x; 1.0092x over previous
; #define PG8_LAS __attribute__((address_space(3)))
; __device__ __forceinline__ float row_rstd(const float* slots, int row) {
;     const f32x4* s = (const f32x4*)(slots + (size_t)row * 16);
;     const f32x4 a = s[0], b = s[1], c = s[2], d = s[3];
;     const f32x4 t = (a + b) + (c + d);
;     const float ss = (t[0] + t[1]) + (t[2] + t[3]);
;     return __builtin_amdgcn_rsqf(ss * (1.0f / 1024.0f) + 1e-6f);
; }
; __device__ __forceinline__ void load_rs(const float* slots, int rowbase, int fr, int fq, float scale, float (&rs)[2][4]) {
;     float loc[2];
; #pragma unroll
;     for (int ai = 0; ai < 2; ++ai) loc[ai] = scale * row_rstd(slots, rowbase + ai * HALF + fq * 16 + fr);
; #pragma unroll
;     for (int ai = 0; ai < 2; ++ai)
; #pragma unroll
;         for (int m = 0; m < 4; ++m) rs[ai][m] = __shfl(loc[ai], m * 16 + fr);
;     __device__ __forceinline__ void operator()(const f32x4 (&acc)[2][2][4][2], const Unit& u, int wr, int wc, int fr, int fq) const {
;         constexpr int FF = 2816, FF2 = 5632;
;         const int lcol = wc * 32 + 8 * fq, gcol = u.pn * HALF + lcol;
;         float rs[2][4];
;         load_rs(slots, u.pm * BM + wr * 64, fr, fq, 1.0f, rs);
;         if (fr >= 14) {
; #pragma unroll
;             for (int ai = 0; ai < 2; ++ai)
; #pragma unroll
;                 for (int bj = 0; bj < 2; ++bj)
; #pragma unroll
;                     for (int n = 0; n < 2; ++n) { const f32x4 x = acc[ai][bj][3][n] * rs[ai][3];
;                         *(PG8_LAS f32x4*)(halo + ((ai * 2 + wr) * 2 + (fr - 14)) * 256 + bj * HALF + lcol + 4 * n) = x;
;                         if (ai == 1 && wr == 1) *(f32x4*)(rawh + (size_t)(u.pm * 2 + (fr - 14)) * FF2 + bj * FF + gcol + 4 * n) = x; }
;         }
;         f32x4 w0[2], w1[2], w2[2], bb[2];
; #pragma unroll
;         for (int bj = 0; bj < 2; ++bj) { const int col = bj * FF + gcol;
;             w0[bj] = *(const f32x4*)(cw + col); w1[bj] = *(const f32x4*)(cw + FF2 + col); w2[bj] = *(const f32x4*)(cw + 2 * FF2 + col); bb[bj] = *(const f32x4*)(cb + col); }
;         asm volatile("s_waitcnt lgkmcnt(0)" ::: "memory"); __builtin_amdgcn_s_barrier(); asm volatile("" ::: "memory");
;         unsigned pk_lo[2][4][2];
; #pragma unroll
;         for (int n = 0; n < 2; ++n) {
;             if (n == 1) {
; #pragma unroll
;                 for (int bj = 0; bj < 2; ++bj) { const int col = bj * FF + gcol + 4;
.LBB0_900:
	v_readlane_b32 s18, v255, 37
	v_readlane_b32 s19, v255, 38
	s_lshl_b32 s5, s71, 8
	s_add_i32 s5, s5, s8
	s_lshl_b32 s11, s71, 1
	s_movk_i32 s29, 0x1600
	s_mov_b32 s100, 0xbfb8aa3b
	v_or_b32_e32 v227, s5, v209
	v_lshl_or_b32 v231, s69, 7, v208
	v_lshlrev_b32_e32 v227, 6, v227
	v_lshlrev_b32_e32 v231, 2, v231
	v_add_u32_e32 v229, 0x2000, v227
	v_add_u32_e32 v233, 0x2c00, v231
	global_load_dwordx4 v[160:163], v227, s[26:27]
	global_load_dwordx4 v[164:167], v227, s[26:27] offset:16
	global_load_dwordx4 v[178:181], v227, s[26:27] offset:32
	global_load_dwordx4 v[182:185], v227, s[26:27] offset:48
	global_load_dwordx4 v[186:189], v229, s[26:27]
	global_load_dwordx4 v[194:197], v229, s[26:27] offset:16
	global_load_dwordx4 v[198:201], v229, s[26:27] offset:32
	global_load_dwordx4 v[202:205], v229, s[26:27] offset:48
	global_load_dwordx4 v[128:131], v231, s[14:15]
	global_load_dwordx4 v[132:135], v231, s[16:17]
	global_load_dwordx4 v[136:139], v231, s[92:93]
	global_load_dwordx4 v[140:143], v231, s[60:61]
	global_load_dwordx4 v[144:147], v233, s[14:15]
	global_load_dwordx4 v[148:151], v233, s[16:17]
	global_load_dwordx4 v[152:155], v233, s[92:93]
	global_load_dwordx4 v[156:159], v233, s[60:61]
	v_or_b32_e32 v237, s5, v206
	v_lshrrev_b32_e32 v243, 1, v231
	v_add_u32_e32 v239, s11, v206
	v_mad_u32_u24 v237, v237, s29, v243
	v_mad_u32_u24 v239, v239, s70, v231
	v_lshlrev_b32_e32 v235, 2, v206
	v_add_u32_e32 v241, 0x2c00, v239
	s_waitcnt vmcnt(8)
	v_pk_add_f32 v[162:163], v[162:163], v[166:167]
	v_pk_add_f32 v[188:189], v[188:189], v[196:197]
	v_pk_add_f32 v[160:161], v[160:161], v[164:165]
	v_pk_add_f32 v[186:187], v[186:187], v[194:195]
	v_pk_add_f32 v[164:165], v[180:181], v[184:185]
	v_pk_add_f32 v[194:195], v[200:201], v[204:205]
	v_pk_add_f32 v[166:167], v[178:179], v[182:183]
	v_pk_add_f32 v[196:197], v[198:199], v[202:203]
	v_pk_add_f32 v[162:163], v[162:163], v[164:165]
	v_pk_add_f32 v[188:189], v[188:189], v[194:195]
	v_pk_add_f32 v[160:161], v[160:161], v[166:167]
	v_pk_add_f32 v[186:187], v[186:187], v[196:197]
	v_add_f32_e32 v160, v160, v161
	v_add_f32_e32 v186, v186, v187
	v_add_f32_e32 v161, v162, v163
	v_add_f32_e32 v187, v188, v189
	v_add_f32_e32 v160, v160, v161
	v_add_f32_e32 v186, v186, v187
	v_fmamk_f32 v160, v160, 0x3a800000, v244
	v_fmamk_f32 v186, v186, 0x3a800000, v244
	v_rsq_f32_e32 v160, v160
	v_rsq_f32_e32 v186, v186
	ds_bpermute_b32 v226, v235, v160
	ds_bpermute_b32 v228, v235, v160 offset:64
	ds_bpermute_b32 v230, v235, v160 offset:128
	ds_bpermute_b32 v232, v235, v160 offset:192
	ds_bpermute_b32 v234, v235, v186
	ds_bpermute_b32 v236, v235, v186 offset:64
	ds_bpermute_b32 v238, v235, v186 offset:128
	ds_bpermute_b32 v240, v235, v186 offset:192
	s_waitcnt lgkmcnt(0)
	v_pk_mul_f32 v[100:101], v[100:101], v[232:233] op_sel_hi:[1,0]
	v_pk_mul_f32 v[102:103], v[102:103], v[232:233] op_sel_hi:[1,0]
	v_pk_mul_f32 v[36:37], v[36:37], v[232:233] op_sel_hi:[1,0]
	v_pk_mul_f32 v[38:39], v[38:39], v[232:233] op_sel_hi:[1,0]
	v_pk_mul_f32 v[96:97], v[96:97], v[232:233] op_sel_hi:[1,0]
	v_pk_mul_f32 v[98:99], v[98:99], v[232:233] op_sel_hi:[1,0]
	v_pk_mul_f32 v[32:33], v[32:33], v[232:233] op_sel_hi:[1,0]
	v_pk_mul_f32 v[34:35], v[34:35], v[232:233] op_sel_hi:[1,0]
	v_pk_mul_f32 v[68:69], v[68:69], v[240:241] op_sel_hi:[1,0]
	v_pk_mul_f32 v[70:71], v[70:71], v[240:241] op_sel_hi:[1,0]
	v_pk_mul_f32 v[4:5], v[4:5], v[240:241] op_sel_hi:[1,0]
	v_pk_mul_f32 v[6:7], v[6:7], v[240:241] op_sel_hi:[1,0]
	v_pk_mul_f32 v[64:65], v[64:65], v[240:241] op_sel_hi:[1,0]
	v_pk_mul_f32 v[66:67], v[66:67], v[240:241] op_sel_hi:[1,0]
	v_pk_mul_f32 v[0:1], v[0:1], v[240:241] op_sel_hi:[1,0]
	v_pk_mul_f32 v[2:3], v[2:3], v[240:241] op_sel_hi:[1,0]
	s_mov_b64 s[0:1], exec
	s_andn2_b64 exec, exec, s[40:41]
	ds_write_b128 v211, v[100:103]
	ds_write_b128 v211, v[36:39] offset:16
	ds_write_b128 v211, v[96:99] offset:512
	ds_write_b128 v211, v[32:35] offset:528
	ds_write_b128 v211, v[68:71] offset:4096
	ds_write_b128 v211, v[4:7] offset:4112
	ds_write_b128 v211, v[64:67] offset:4608
	ds_write_b128 v211, v[0:3] offset:4624
	s_mov_b64 exec, s[0:1]
	s_waitcnt lgkmcnt(0)
	s_barrier
	s_and_b64 vcc, exec, s[94:95]
	s_cbranch_vccnz .Lp7_hz0
	ds_read_b128 v[160:163], v213
	ds_read_b128 v[164:167], v213 offset:512
	s_branch .Lp7_hr0
.Lp7_hz0:
	v_mov_b32_e32 v160, 0
	v_mov_b32_e32 v161, 0
	v_mov_b32_e32 v162, 0
	v_mov_b32_e32 v163, 0
	v_mov_b32_e32 v164, 0
	v_mov_b32_e32 v165, 0
	v_mov_b32_e32 v166, 0
	v_mov_b32_e32 v167, 0
; #define PG8_LAS __attribute__((address_space(3)))
; __device__ __forceinline__ unsigned cvt_pk_bf16(float lo, float hi) { unsigned r; asm volatile("v_cvt_pk_bf16_f32 %0, %1, %2" : "=v"(r) : "v"(lo), "v"(hi)); return r; }
; __device__ __forceinline__ float dpp_ror1(float x) { return __int_as_float(__builtin_amdgcn_update_dpp(0, __float_as_int(x), 0x121, 0xf, 0xf, false)); }
; __device__ __forceinline__ float dpp_ror2(float x) { return __int_as_float(__builtin_amdgcn_update_dpp(0, __float_as_int(x), 0x122, 0xf, 0xf, false)); }
;     __device__ __forceinline__ void operator()(const f32x4 (&acc)[2][2][4][2], const Unit& u, int wr, int wc, int fr, int fq) const {
;     ...
;                 f32x4 pg[2]; const int pb = ai * 2 + wr - 1;
; #pragma unroll
;                 for (int bj = 0; bj < 2; ++bj) { pg[bj] = (f32x4){0.f, 0.f, 0.f, 0.f};
;                     if (pb >= 0 && fr >= 14) pg[bj] = *(const PG8_LAS f32x4*)(halo + (pb * 2 + (fr - 14)) * 256 + bj * HALF + lcol + 4 * n); }
; #pragma unroll
;                 for (int m = 0; m < 4; ++m) {
;                     f32x4 cur[2], h[2];
; #pragma unroll
;                     for (int bj = 0; bj < 2; ++bj) { cur[bj] = acc[ai][bj][m][n] * rs[ai][m]; f32x4 x1, x2;
; #pragma unroll
;                         for (int e = 0; e < 4; ++e) { const float c1 = dpp_ror1(cur[bj][e]), p1 = dpp_ror1(pg[bj][e]), c2 = dpp_ror2(cur[bj][e]), p2 = dpp_ror2(pg[bj][e]);
;                             x1[e] = fr >= 1 ? c1 : p1; x2[e] = fr >= 2 ? c2 : p2; }
;                         h[bj] = bb[bj] + w0[bj] * x2 + w1[bj] * x1 + w2[bj] * cur[bj]; }
;                     if (ai == 0 && wr == 0 && m == 0 && fr < 2) {
;                         *(f32x4*)(hc0 + (size_t)(u.pm * 2 + fr) * FF2 + gcol + 4 * n) = h[0]; *(f32x4*)(hc0 + (size_t)(u.pm * 2 + fr) * FF2 + FF + gcol + 4 * n) = h[1]; }
;                     f32x4 a;
; #pragma unroll
;                     for (int e = 0; e < 4; ++e) { const float g = h[0][e]; a[e] = g * __builtin_amdgcn_rcpf(1.0f + __builtin_amdgcn_exp2f(-1.4426950408889634f * g)) * h[1][e]; }
;                     const unsigned p0 = cvt_pk_bf16(a[0], a[1]), p1 = cvt_pk_bf16(a[2], a[3]);
;                     if (n == 0) { pk_lo[ai][m][0] = p0; pk_lo[ai][m][1] = p1; }
.Lp7_hr0:
	ds_read_b128 v[178:181], v214
	ds_read_b128 v[182:185], v214 offset:512
	s_waitcnt vmcnt(0) lgkmcnt(0)
	v_pk_mul_f32 v[124:125], v[124:125], v[226:227] op_sel_hi:[1,0]
	v_pk_mul_f32 v[126:127], v[126:127], v[226:227] op_sel_hi:[1,0]
	v_pk_mul_f32 v[120:121], v[120:121], v[226:227] op_sel_hi:[1,0]
	v_pk_mul_f32 v[122:123], v[122:123], v[226:227] op_sel_hi:[1,0]
	v_pk_fma_f32 v[220:221], v[136:137], v[124:125], v[140:141]
	v_pk_fma_f32 v[222:223], v[138:139], v[126:127], v[142:143]
	v_pk_fma_f32 v[248:249], v[152:153], v[120:121], v[156:157]
	v_pk_fma_f32 v[250:251], v[154:155], v[122:123], v[158:159]
	v_fmac_f32_dpp v220, v124, v132 row_shr:1 row_mask:0xf bank_mask:0xf
	v_fmac_f32_dpp v221, v125, v133 row_shr:1 row_mask:0xf bank_mask:0xf
	v_fmac_f32_dpp v222, v126, v134 row_shr:1 row_mask:0xf bank_mask:0xf
	v_fmac_f32_dpp v223, v127, v135 row_shr:1 row_mask:0xf bank_mask:0xf
	v_fmac_f32_dpp v248, v120, v148 row_shr:1 row_mask:0xf bank_mask:0xf
	v_fmac_f32_dpp v249, v121, v149 row_shr:1 row_mask:0xf bank_mask:0xf
	v_fmac_f32_dpp v250, v122, v150 row_shr:1 row_mask:0xf bank_mask:0xf
	v_fmac_f32_dpp v251, v123, v151 row_shr:1 row_mask:0xf bank_mask:0xf
	v_fmac_f32_dpp v220, v160, v132 row_shl:15 row_mask:0xf bank_mask:0xf
	v_fmac_f32_dpp v221, v161, v133 row_shl:15 row_mask:0xf bank_mask:0xf
	v_fmac_f32_dpp v222, v162, v134 row_shl:15 row_mask:0xf bank_mask:0xf
	v_fmac_f32_dpp v223, v163, v135 row_shl:15 row_mask:0xf bank_mask:0xf
	v_fmac_f32_dpp v248, v164, v148 row_shl:15 row_mask:0xf bank_mask:0xf
	v_fmac_f32_dpp v249, v165, v149 row_shl:15 row_mask:0xf bank_mask:0xf
	v_fmac_f32_dpp v250, v166, v150 row_shl:15 row_mask:0xf bank_mask:0xf
	v_fmac_f32_dpp v251, v167, v151 row_shl:15 row_mask:0xf bank_mask:0xf
	v_fmac_f32_dpp v220, v124, v128 row_shr:2 row_mask:0xf bank_mask:0xf
	v_fmac_f32_dpp v221, v125, v129 row_shr:2 row_mask:0xf bank_mask:0xf
	v_fmac_f32_dpp v222, v126, v130 row_shr:2 row_mask:0xf bank_mask:0xf
	v_fmac_f32_dpp v223, v127, v131 row_shr:2 row_mask:0xf bank_mask:0xf
	v_fmac_f32_dpp v248, v120, v144 row_shr:2 row_mask:0xf bank_mask:0xf
	v_fmac_f32_dpp v249, v121, v145 row_shr:2 row_mask:0xf bank_mask:0xf
	v_fmac_f32_dpp v250, v122, v146 row_shr:2 row_mask:0xf bank_mask:0xf
	v_fmac_f32_dpp v251, v123, v147 row_shr:2 row_mask:0xf bank_mask:0xf
	v_fmac_f32_dpp v220, v160, v128 row_shl:14 row_mask:0xf bank_mask:0xf
	v_fmac_f32_dpp v221, v161, v129 row_shl:14 row_mask:0xf bank_mask:0xf
	v_fmac_f32_dpp v222, v162, v130 row_shl:14 row_mask:0xf bank_mask:0xf
	v_fmac_f32_dpp v223, v163, v131 row_shl:14 row_mask:0xf bank_mask:0xf
	v_fmac_f32_dpp v248, v164, v144 row_shl:14 row_mask:0xf bank_mask:0xf
	v_fmac_f32_dpp v249, v165, v145 row_shl:14 row_mask:0xf bank_mask:0xf
	v_fmac_f32_dpp v250, v166, v146 row_shl:14 row_mask:0xf bank_mask:0xf
	v_fmac_f32_dpp v251, v167, v147 row_shl:14 row_mask:0xf bank_mask:0xf
	s_and_saveexec_b64 s[0:1], s[12:13]
	global_store_dwordx4 v239, v[220:223], s[84:85]
	global_store_dwordx4 v241, v[248:251], s[84:85]
	s_or_b64 exec, exec, s[0:1]
	v_pk_mul_f32 v[224:225], v[220:221], s[100:101] op_sel_hi:[1,0]
	v_pk_mul_f32 v[190:191], v[222:223], s[100:101] op_sel_hi:[1,0]
	v_exp_f32_e32 v224, v224
	v_exp_f32_e32 v225, v225
	v_exp_f32_e32 v190, v190
	v_exp_f32_e32 v191, v191
	v_pk_mul_f32 v[220:221], v[220:221], v[248:249]
	v_pk_mul_f32 v[222:223], v[222:223], v[250:251]
	v_pk_add_f32 v[224:225], v[224:225], 1.0 op_sel_hi:[1,0]
	v_pk_add_f32 v[190:191], v[190:191], 1.0 op_sel_hi:[1,0]
	v_rcp_f32_e32 v224, v224
	v_rcp_f32_e32 v225, v225
	v_rcp_f32_e32 v190, v190
	v_rcp_f32_e32 v191, v191
	v_pk_mul_f32 v[220:221], v[220:221], v[224:225]
	v_pk_mul_f32 v[222:223], v[222:223], v[190:191]
	v_cvt_pk_bf16_f32 v186, v220, v221
	v_cvt_pk_bf16_f32 v187, v222, v223
	v_pk_mul_f32 v[116:117], v[116:117], v[228:229] op_sel_hi:[1,0]
	v_pk_mul_f32 v[118:119], v[118:119], v[228:229] op_sel_hi:[1,0]
	v_pk_mul_f32 v[112:113], v[112:113], v[228:229] op_sel_hi:[1,0]
	v_pk_mul_f32 v[114:115], v[114:115], v[228:229] op_sel_hi:[1,0]
	v_pk_fma_f32 v[220:221], v[136:137], v[116:117], v[140:141]
	v_pk_fma_f32 v[222:223], v[138:139], v[118:119], v[142:143]
	v_pk_fma_f32 v[248:249], v[152:153], v[112:113], v[156:157]
	v_pk_fma_f32 v[250:251], v[154:155], v[114:115], v[158:159]
	v_fmac_f32_dpp v220, v116, v132 row_shr:1 row_mask:0xf bank_mask:0xf
	v_fmac_f32_dpp v221, v117, v133 row_shr:1 row_mask:0xf bank_mask:0xf
	v_fmac_f32_dpp v222, v118, v134 row_shr:1 row_mask:0xf bank_mask:0xf
	v_fmac_f32_dpp v223, v119, v135 row_shr:1 row_mask:0xf bank_mask:0xf
	v_fmac_f32_dpp v248, v112, v148 row_shr:1 row_mask:0xf bank_mask:0xf
	v_fmac_f32_dpp v249, v113, v149 row_shr:1 row_mask:0xf bank_mask:0xf
	v_fmac_f32_dpp v250, v114, v150 row_shr:1 row_mask:0xf bank_mask:0xf
	v_fmac_f32_dpp v251, v115, v151 row_shr:1 row_mask:0xf bank_mask:0xf
	v_fmac_f32_dpp v220, v124, v132 row_shl:15 row_mask:0xf bank_mask:0xf
	v_fmac_f32_dpp v221, v125, v133 row_shl:15 row_mask:0xf bank_mask:0xf
	v_fmac_f32_dpp v222, v126, v134 row_shl:15 row_mask:0xf bank_mask:0xf
	v_fmac_f32_dpp v223, v127, v135 row_shl:15 row_mask:0xf bank_mask:0xf
	v_fmac_f32_dpp v248, v120, v148 row_shl:15 row_mask:0xf bank_mask:0xf
	v_fmac_f32_dpp v249, v121, v149 row_shl:15 row_mask:0xf bank_mask:0xf
	v_fmac_f32_dpp v250, v122, v150 row_shl:15 row_mask:0xf bank_mask:0xf
	v_fmac_f32_dpp v251, v123, v151 row_shl:15 row_mask:0xf bank_mask:0xf
	v_fmac_f32_dpp v220, v116, v128 row_shr:2 row_mask:0xf bank_mask:0xf
	v_fmac_f32_dpp v221, v117, v129 row_shr:2 row_mask:0xf bank_mask:0xf
	v_fmac_f32_dpp v222, v118, v130 row_shr:2 row_mask:0xf bank_mask:0xf
	v_fmac_f32_dpp v223, v119, v131 row_shr:2 row_mask:0xf bank_mask:0xf
; __device__ __forceinline__ unsigned cvt_pk_bf16(float lo, float hi) { unsigned r; asm volatile("v_cvt_pk_bf16_f32 %0, %1, %2" : "=v"(r) : "v"(lo), "v"(hi)); return r; }
; __device__ __forceinline__ float dpp_ror1(float x) { return __int_as_float(__builtin_amdgcn_update_dpp(0, __float_as_int(x), 0x121, 0xf, 0xf, false)); }
; __device__ __forceinline__ float dpp_ror2(float x) { return __int_as_float(__builtin_amdgcn_update_dpp(0, __float_as_int(x), 0x122, 0xf, 0xf, false)); }
;     __device__ __forceinline__ void operator()(const f32x4 (&acc)[2][2][4][2], const Unit& u, int wr, int wc, int fr, int fq) const {
;     ...
;                 for (int m = 0; m < 4; ++m) {
;                     f32x4 cur[2], h[2];
; #pragma unroll
;                     for (int bj = 0; bj < 2; ++bj) { cur[bj] = acc[ai][bj][m][n] * rs[ai][m]; f32x4 x1, x2;
; #pragma unroll
;                         for (int e = 0; e < 4; ++e) { const float c1 = dpp_ror1(cur[bj][e]), p1 = dpp_ror1(pg[bj][e]), c2 = dpp_ror2(cur[bj][e]), p2 = dpp_ror2(pg[bj][e]);
;                             x1[e] = fr >= 1 ? c1 : p1; x2[e] = fr >= 2 ? c2 : p2; }
;                         h[bj] = bb[bj] + w0[bj] * x2 + w1[bj] * x1 + w2[bj] * cur[bj]; }
;                     if (ai == 0 && wr == 0 && m == 0 && fr < 2) {
;                         *(f32x4*)(hc0 + (size_t)(u.pm * 2 + fr) * FF2 + gcol + 4 * n) = h[0]; *(f32x4*)(hc0 + (size_t)(u.pm * 2 + fr) * FF2 + FF + gcol + 4 * n) = h[1]; }
;                     f32x4 a;
; #pragma unroll
;                     for (int e = 0; e < 4; ++e) { const float g = h[0][e]; a[e] = g * __builtin_amdgcn_rcpf(1.0f + __builtin_amdgcn_exp2f(-1.4426950408889634f * g)) * h[1][e]; }
;                     const unsigned p0 = cvt_pk_bf16(a[0], a[1]), p1 = cvt_pk_bf16(a[2], a[3]);
;                     if (n == 0) { pk_lo[ai][m][0] = p0; pk_lo[ai][m][1] = p1; }
	v_fmac_f32_dpp v248, v112, v144 row_shr:2 row_mask:0xf bank_mask:0xf
	v_fmac_f32_dpp v249, v113, v145 row_shr:2 row_mask:0xf bank_mask:0xf
	v_fmac_f32_dpp v250, v114, v146 row_shr:2 row_mask:0xf bank_mask:0xf
	v_fmac_f32_dpp v251, v115, v147 row_shr:2 row_mask:0xf bank_mask:0xf
	v_fmac_f32_dpp v220, v124, v128 row_shl:14 row_mask:0xf bank_mask:0xf
	v_fmac_f32_dpp v221, v125, v129 row_shl:14 row_mask:0xf bank_mask:0xf
	v_fmac_f32_dpp v222, v126, v130 row_shl:14 row_mask:0xf bank_mask:0xf
	v_fmac_f32_dpp v223, v127, v131 row_shl:14 row_mask:0xf bank_mask:0xf
	v_fmac_f32_dpp v248, v120, v144 row_shl:14 row_mask:0xf bank_mask:0xf
	v_fmac_f32_dpp v249, v121, v145 row_shl:14 row_mask:0xf bank_mask:0xf
	v_fmac_f32_dpp v250, v122, v146 row_shl:14 row_mask:0xf bank_mask:0xf
	v_fmac_f32_dpp v251, v123, v147 row_shl:14 row_mask:0xf bank_mask:0xf
	v_pk_mul_f32 v[224:225], v[220:221], s[100:101] op_sel_hi:[1,0]
	v_pk_mul_f32 v[190:191], v[222:223], s[100:101] op_sel_hi:[1,0]
	v_exp_f32_e32 v224, v224
	v_exp_f32_e32 v225, v225
	v_exp_f32_e32 v190, v190
	v_exp_f32_e32 v191, v191
	v_pk_mul_f32 v[220:221], v[220:221], v[248:249]
	v_pk_mul_f32 v[222:223], v[222:223], v[250:251]
	v_pk_add_f32 v[224:225], v[224:225], 1.0 op_sel_hi:[1,0]
	v_pk_add_f32 v[190:191], v[190:191], 1.0 op_sel_hi:[1,0]
	v_rcp_f32_e32 v224, v224
	v_rcp_f32_e32 v225, v225
	v_rcp_f32_e32 v190, v190
	v_rcp_f32_e32 v191, v191
	v_pk_mul_f32 v[220:221], v[220:221], v[224:225]
	v_pk_mul_f32 v[222:223], v[222:223], v[190:191]
	v_cvt_pk_bf16_f32 v194, v220, v221
	v_cvt_pk_bf16_f32 v195, v222, v223
	v_pk_mul_f32 v[108:109], v[108:109], v[230:231] op_sel_hi:[1,0]
	v_pk_mul_f32 v[110:111], v[110:111], v[230:231] op_sel_hi:[1,0]
	v_pk_mul_f32 v[104:105], v[104:105], v[230:231] op_sel_hi:[1,0]
	v_pk_mul_f32 v[106:107], v[106:107], v[230:231] op_sel_hi:[1,0]
	v_pk_fma_f32 v[220:221], v[136:137], v[108:109], v[140:141]
	v_pk_fma_f32 v[222:223], v[138:139], v[110:111], v[142:143]
	v_pk_fma_f32 v[248:249], v[152:153], v[104:105], v[156:157]
	v_pk_fma_f32 v[250:251], v[154:155], v[106:107], v[158:159]
	v_fmac_f32_dpp v220, v108, v132 row_shr:1 row_mask:0xf bank_mask:0xf
	v_fmac_f32_dpp v221, v109, v133 row_shr:1 row_mask:0xf bank_mask:0xf
	v_fmac_f32_dpp v222, v110, v134 row_shr:1 row_mask:0xf bank_mask:0xf
	v_fmac_f32_dpp v223, v111, v135 row_shr:1 row_mask:0xf bank_mask:0xf
	v_fmac_f32_dpp v248, v104, v148 row_shr:1 row_mask:0xf bank_mask:0xf
	v_fmac_f32_dpp v249, v105, v149 row_shr:1 row_mask:0xf bank_mask:0xf
	v_fmac_f32_dpp v250, v106, v150 row_shr:1 row_mask:0xf bank_mask:0xf
	v_fmac_f32_dpp v251, v107, v151 row_shr:1 row_mask:0xf bank_mask:0xf
	v_fmac_f32_dpp v220, v116, v132 row_shl:15 row_mask:0xf bank_mask:0xf
	v_fmac_f32_dpp v221, v117, v133 row_shl:15 row_mask:0xf bank_mask:0xf
	v_fmac_f32_dpp v222, v118, v134 row_shl:15 row_mask:0xf bank_mask:0xf
	v_fmac_f32_dpp v223, v119, v135 row_shl:15 row_mask:0xf bank_mask:0xf
	v_fmac_f32_dpp v248, v112, v148 row_shl:15 row_mask:0xf bank_mask:0xf
	v_fmac_f32_dpp v249, v113, v149 row_shl:15 row_mask:0xf bank_mask:0xf
	v_fmac_f32_dpp v250, v114, v150 row_shl:15 row_mask:0xf bank_mask:0xf
	v_fmac_f32_dpp v251, v115, v151 row_shl:15 row_mask:0xf bank_mask:0xf
	v_fmac_f32_dpp v220, v108, v128 row_shr:2 row_mask:0xf bank_mask:0xf
	v_fmac_f32_dpp v221, v109, v129 row_shr:2 row_mask:0xf bank_mask:0xf
	v_fmac_f32_dpp v222, v110, v130 row_shr:2 row_mask:0xf bank_mask:0xf
	v_fmac_f32_dpp v223, v111, v131 row_shr:2 row_mask:0xf bank_mask:0xf
	v_fmac_f32_dpp v248, v104, v144 row_shr:2 row_mask:0xf bank_mask:0xf
	v_fmac_f32_dpp v249, v105, v145 row_shr:2 row_mask:0xf bank_mask:0xf
	v_fmac_f32_dpp v250, v106, v146 row_shr:2 row_mask:0xf bank_mask:0xf
	v_fmac_f32_dpp v251, v107, v147 row_shr:2 row_mask:0xf bank_mask:0xf
	v_fmac_f32_dpp v220, v116, v128 row_shl:14 row_mask:0xf bank_mask:0xf
	v_fmac_f32_dpp v221, v117, v129 row_shl:14 row_mask:0xf bank_mask:0xf
	v_fmac_f32_dpp v222, v118, v130 row_shl:14 row_mask:0xf bank_mask:0xf
	v_fmac_f32_dpp v223, v119, v131 row_shl:14 row_mask:0xf bank_mask:0xf
	v_fmac_f32_dpp v248, v112, v144 row_shl:14 row_mask:0xf bank_mask:0xf
	v_fmac_f32_dpp v249, v113, v145 row_shl:14 row_mask:0xf bank_mask:0xf
	v_fmac_f32_dpp v250, v114, v146 row_shl:14 row_mask:0xf bank_mask:0xf
	v_fmac_f32_dpp v251, v115, v147 row_shl:14 row_mask:0xf bank_mask:0xf
	v_pk_mul_f32 v[224:225], v[220:221], s[100:101] op_sel_hi:[1,0]
	v_pk_mul_f32 v[190:191], v[222:223], s[100:101] op_sel_hi:[1,0]
	v_exp_f32_e32 v224, v224
	v_exp_f32_e32 v225, v225
	v_exp_f32_e32 v190, v190
	v_exp_f32_e32 v191, v191
	v_pk_mul_f32 v[220:221], v[220:221], v[248:249]
	v_pk_mul_f32 v[222:223], v[222:223], v[250:251]
	v_pk_add_f32 v[224:225], v[224:225], 1.0 op_sel_hi:[1,0]
	v_pk_add_f32 v[190:191], v[190:191], 1.0 op_sel_hi:[1,0]
	v_rcp_f32_e32 v224, v224
	v_rcp_f32_e32 v225, v225
	v_rcp_f32_e32 v190, v190
	v_rcp_f32_e32 v191, v191
	v_pk_mul_f32 v[220:221], v[220:221], v[224:225]
	v_pk_mul_f32 v[222:223], v[222:223], v[190:191]
	v_cvt_pk_bf16_f32 v198, v220, v221
	v_cvt_pk_bf16_f32 v199, v222, v223
	v_pk_fma_f32 v[220:221], v[136:137], v[100:101], v[140:141]
	v_pk_fma_f32 v[222:223], v[138:139], v[102:103], v[142:143]
	v_pk_fma_f32 v[248:249], v[152:153], v[96:97], v[156:157]
	v_pk_fma_f32 v[250:251], v[154:155], v[98:99], v[158:159]
	v_fmac_f32_dpp v220, v100, v132 row_shr:1 row_mask:0xf bank_mask:0xf
	v_fmac_f32_dpp v221, v101, v133 row_shr:1 row_mask:0xf bank_mask:0xf
	v_fmac_f32_dpp v222, v102, v134 row_shr:1 row_mask:0xf bank_mask:0xf
	v_fmac_f32_dpp v223, v103, v135 row_shr:1 row_mask:0xf bank_mask:0xf
	v_fmac_f32_dpp v248, v96, v148 row_shr:1 row_mask:0xf bank_mask:0xf
; #define PG8_LAS __attribute__((address_space(3)))
; __device__ __forceinline__ unsigned cvt_pk_bf16(float lo, float hi) { unsigned r; asm volatile("v_cvt_pk_bf16_f32 %0, %1, %2" : "=v"(r) : "v"(lo), "v"(hi)); return r; }
;     __device__ __forceinline__ void operator()(const f32x4 (&acc)[2][2][4][2], const Unit& u, int wr, int wc, int fr, int fq) const {
;     ...
;             if (n == 1) {
; #pragma unroll
;                 for (int bj = 0; bj < 2; ++bj) { const int col = bj * FF + gcol + 4;
;                     w0[bj] = *(const f32x4*)(cw + col); w1[bj] = *(const f32x4*)(cw + FF2 + col); w2[bj] = *(const f32x4*)(cw + 2 * FF2 + col); bb[bj] = *(const f32x4*)(cb + col); } }
; #pragma unroll
;             for (int ai = 0; ai < 2; ++ai) {
;                 f32x4 pg[2]; const int pb = ai * 2 + wr - 1;
; #pragma unroll
;                 for (int bj = 0; bj < 2; ++bj) { pg[bj] = (f32x4){0.f, 0.f, 0.f, 0.f};
;                     if (pb >= 0 && fr >= 14) pg[bj] = *(const PG8_LAS f32x4*)(halo + (pb * 2 + (fr - 14)) * 256 + bj * HALF + lcol + 4 * n); }
; #pragma unroll
;                 for (int m = 0; m < 4; ++m) {
;                     f32x4 cur[2], h[2];
; #pragma unroll
;                     for (int bj = 0; bj < 2; ++bj) { cur[bj] = acc[ai][bj][m][n] * rs[ai][m]; f32x4 x1, x2;
; #pragma unroll
;                         for (int e = 0; e < 4; ++e) { const float c1 = dpp_ror1(cur[bj][e]), p1 = dpp_ror1(pg[bj][e]), c2 = dpp_ror2(cur[bj][e]), p2 = dpp_ror2(pg[bj][e]);
;                             x1[e] = fr >= 1 ? c1 : p1; x2[e] = fr >= 2 ? c2 : p2; }
;                         h[bj] = bb[bj] + w0[bj] * x2 + w1[bj] * x1 + w2[bj] * cur[bj]; }
;                     if (ai == 0 && wr == 0 && m == 0 && fr < 2) {
;                         *(f32x4*)(hc0 + (size_t)(u.pm * 2 + fr) * FF2 + gcol + 4 * n) = h[0]; *(f32x4*)(hc0 + (size_t)(u.pm * 2 + fr) * FF2 + FF + gcol + 4 * n) = h[1]; }
;                     f32x4 a;
; #pragma unroll
;                     for (int e = 0; e < 4; ++e) { const float g = h[0][e]; a[e] = g * __builtin_amdgcn_rcpf(1.0f + __builtin_amdgcn_exp2f(-1.4426950408889634f * g)) * h[1][e]; }
;                     const unsigned p0 = cvt_pk_bf16(a[0], a[1]), p1 = cvt_pk_bf16(a[2], a[3]);
;                     if (n == 0) { pk_lo[ai][m][0] = p0; pk_lo[ai][m][1] = p1; }
	v_fmac_f32_dpp v249, v97, v149 row_shr:1 row_mask:0xf bank_mask:0xf
	v_fmac_f32_dpp v250, v98, v150 row_shr:1 row_mask:0xf bank_mask:0xf
	v_fmac_f32_dpp v251, v99, v151 row_shr:1 row_mask:0xf bank_mask:0xf
	v_fmac_f32_dpp v220, v108, v132 row_shl:15 row_mask:0xf bank_mask:0xf
	v_fmac_f32_dpp v221, v109, v133 row_shl:15 row_mask:0xf bank_mask:0xf
	v_fmac_f32_dpp v222, v110, v134 row_shl:15 row_mask:0xf bank_mask:0xf
	v_fmac_f32_dpp v223, v111, v135 row_shl:15 row_mask:0xf bank_mask:0xf
	v_fmac_f32_dpp v248, v104, v148 row_shl:15 row_mask:0xf bank_mask:0xf
	v_fmac_f32_dpp v249, v105, v149 row_shl:15 row_mask:0xf bank_mask:0xf
	v_fmac_f32_dpp v250, v106, v150 row_shl:15 row_mask:0xf bank_mask:0xf
	v_fmac_f32_dpp v251, v107, v151 row_shl:15 row_mask:0xf bank_mask:0xf
	v_fmac_f32_dpp v220, v100, v128 row_shr:2 row_mask:0xf bank_mask:0xf
	v_fmac_f32_dpp v221, v101, v129 row_shr:2 row_mask:0xf bank_mask:0xf
	v_fmac_f32_dpp v222, v102, v130 row_shr:2 row_mask:0xf bank_mask:0xf
	v_fmac_f32_dpp v223, v103, v131 row_shr:2 row_mask:0xf bank_mask:0xf
	v_fmac_f32_dpp v248, v96, v144 row_shr:2 row_mask:0xf bank_mask:0xf
	v_fmac_f32_dpp v249, v97, v145 row_shr:2 row_mask:0xf bank_mask:0xf
	v_fmac_f32_dpp v250, v98, v146 row_shr:2 row_mask:0xf bank_mask:0xf
	v_fmac_f32_dpp v251, v99, v147 row_shr:2 row_mask:0xf bank_mask:0xf
	v_fmac_f32_dpp v220, v108, v128 row_shl:14 row_mask:0xf bank_mask:0xf
	v_fmac_f32_dpp v221, v109, v129 row_shl:14 row_mask:0xf bank_mask:0xf
	v_fmac_f32_dpp v222, v110, v130 row_shl:14 row_mask:0xf bank_mask:0xf
	v_fmac_f32_dpp v223, v111, v131 row_shl:14 row_mask:0xf bank_mask:0xf
	v_fmac_f32_dpp v248, v104, v144 row_shl:14 row_mask:0xf bank_mask:0xf
	v_fmac_f32_dpp v249, v105, v145 row_shl:14 row_mask:0xf bank_mask:0xf
	v_fmac_f32_dpp v250, v106, v146 row_shl:14 row_mask:0xf bank_mask:0xf
	v_fmac_f32_dpp v251, v107, v147 row_shl:14 row_mask:0xf bank_mask:0xf
	v_pk_mul_f32 v[224:225], v[220:221], s[100:101] op_sel_hi:[1,0]
	v_pk_mul_f32 v[190:191], v[222:223], s[100:101] op_sel_hi:[1,0]
	v_exp_f32_e32 v224, v224
	v_exp_f32_e32 v225, v225
	v_exp_f32_e32 v190, v190
	v_exp_f32_e32 v191, v191
	v_pk_mul_f32 v[220:221], v[220:221], v[248:249]
	v_pk_mul_f32 v[222:223], v[222:223], v[250:251]
	v_pk_add_f32 v[224:225], v[224:225], 1.0 op_sel_hi:[1,0]
	v_pk_add_f32 v[190:191], v[190:191], 1.0 op_sel_hi:[1,0]
	v_rcp_f32_e32 v224, v224
	v_rcp_f32_e32 v225, v225
	v_rcp_f32_e32 v190, v190
	v_rcp_f32_e32 v191, v191
	v_pk_mul_f32 v[220:221], v[220:221], v[224:225]
	v_pk_mul_f32 v[222:223], v[222:223], v[190:191]
	v_cvt_pk_bf16_f32 v202, v220, v221
	v_cvt_pk_bf16_f32 v203, v222, v223
	global_load_dwordx4 v[124:127], v231, s[14:15] offset:16
	global_load_dwordx4 v[116:119], v231, s[16:17] offset:16
	global_load_dwordx4 v[108:111], v231, s[92:93] offset:16
	global_load_dwordx4 v[100:103], v231, s[60:61] offset:16
	global_load_dwordx4 v[120:123], v233, s[14:15] offset:16
	global_load_dwordx4 v[112:115], v233, s[16:17] offset:16
	global_load_dwordx4 v[104:107], v233, s[92:93] offset:16
	global_load_dwordx4 v[96:99], v233, s[60:61] offset:16
	v_pk_mul_f32 v[92:93], v[92:93], v[234:235] op_sel_hi:[1,0]
	v_pk_mul_f32 v[94:95], v[94:95], v[234:235] op_sel_hi:[1,0]
	v_pk_mul_f32 v[88:89], v[88:89], v[234:235] op_sel_hi:[1,0]
	v_pk_mul_f32 v[90:91], v[90:91], v[234:235] op_sel_hi:[1,0]
	v_pk_fma_f32 v[220:221], v[136:137], v[92:93], v[140:141]
	v_pk_fma_f32 v[222:223], v[138:139], v[94:95], v[142:143]
	v_pk_fma_f32 v[248:249], v[152:153], v[88:89], v[156:157]
	v_pk_fma_f32 v[250:251], v[154:155], v[90:91], v[158:159]
	v_fmac_f32_dpp v220, v92, v132 row_shr:1 row_mask:0xf bank_mask:0xf
	v_fmac_f32_dpp v221, v93, v133 row_shr:1 row_mask:0xf bank_mask:0xf
	v_fmac_f32_dpp v222, v94, v134 row_shr:1 row_mask:0xf bank_mask:0xf
	v_fmac_f32_dpp v223, v95, v135 row_shr:1 row_mask:0xf bank_mask:0xf
	v_fmac_f32_dpp v248, v88, v148 row_shr:1 row_mask:0xf bank_mask:0xf
	v_fmac_f32_dpp v249, v89, v149 row_shr:1 row_mask:0xf bank_mask:0xf
	v_fmac_f32_dpp v250, v90, v150 row_shr:1 row_mask:0xf bank_mask:0xf
	v_fmac_f32_dpp v251, v91, v151 row_shr:1 row_mask:0xf bank_mask:0xf
	v_fmac_f32_dpp v220, v178, v132 row_shl:15 row_mask:0xf bank_mask:0xf
	v_fmac_f32_dpp v221, v179, v133 row_shl:15 row_mask:0xf bank_mask:0xf
	v_fmac_f32_dpp v222, v180, v134 row_shl:15 row_mask:0xf bank_mask:0xf
	v_fmac_f32_dpp v223, v181, v135 row_shl:15 row_mask:0xf bank_mask:0xf
	v_fmac_f32_dpp v248, v182, v148 row_shl:15 row_mask:0xf bank_mask:0xf
	v_fmac_f32_dpp v249, v183, v149 row_shl:15 row_mask:0xf bank_mask:0xf
	v_fmac_f32_dpp v250, v184, v150 row_shl:15 row_mask:0xf bank_mask:0xf
	v_fmac_f32_dpp v251, v185, v151 row_shl:15 row_mask:0xf bank_mask:0xf
	v_fmac_f32_dpp v220, v92, v128 row_shr:2 row_mask:0xf bank_mask:0xf
	v_fmac_f32_dpp v221, v93, v129 row_shr:2 row_mask:0xf bank_mask:0xf
	v_fmac_f32_dpp v222, v94, v130 row_shr:2 row_mask:0xf bank_mask:0xf
	v_fmac_f32_dpp v223, v95, v131 row_shr:2 row_mask:0xf bank_mask:0xf
	v_fmac_f32_dpp v248, v88, v144 row_shr:2 row_mask:0xf bank_mask:0xf
	v_fmac_f32_dpp v249, v89, v145 row_shr:2 row_mask:0xf bank_mask:0xf
	v_fmac_f32_dpp v250, v90, v146 row_shr:2 row_mask:0xf bank_mask:0xf
	v_fmac_f32_dpp v251, v91, v147 row_shr:2 row_mask:0xf bank_mask:0xf
	v_fmac_f32_dpp v220, v178, v128 row_shl:14 row_mask:0xf bank_mask:0xf
	v_fmac_f32_dpp v221, v179, v129 row_shl:14 row_mask:0xf bank_mask:0xf
	v_fmac_f32_dpp v222, v180, v130 row_shl:14 row_mask:0xf bank_mask:0xf
	v_fmac_f32_dpp v223, v181, v131 row_shl:14 row_mask:0xf bank_mask:0xf
	v_fmac_f32_dpp v248, v182, v144 row_shl:14 row_mask:0xf bank_mask:0xf
	v_fmac_f32_dpp v249, v183, v145 row_shl:14 row_mask:0xf bank_mask:0xf
; __device__ __forceinline__ unsigned cvt_pk_bf16(float lo, float hi) { unsigned r; asm volatile("v_cvt_pk_bf16_f32 %0, %1, %2" : "=v"(r) : "v"(lo), "v"(hi)); return r; }
; __device__ __forceinline__ float dpp_ror1(float x) { return __int_as_float(__builtin_amdgcn_update_dpp(0, __float_as_int(x), 0x121, 0xf, 0xf, false)); }
; __device__ __forceinline__ float dpp_ror2(float x) { return __int_as_float(__builtin_amdgcn_update_dpp(0, __float_as_int(x), 0x122, 0xf, 0xf, false)); }
;     __device__ __forceinline__ void operator()(const f32x4 (&acc)[2][2][4][2], const Unit& u, int wr, int wc, int fr, int fq) const {
;     ...
;                 for (int m = 0; m < 4; ++m) {
;                     f32x4 cur[2], h[2];
; #pragma unroll
;                     for (int bj = 0; bj < 2; ++bj) { cur[bj] = acc[ai][bj][m][n] * rs[ai][m]; f32x4 x1, x2;
; #pragma unroll
;                         for (int e = 0; e < 4; ++e) { const float c1 = dpp_ror1(cur[bj][e]), p1 = dpp_ror1(pg[bj][e]), c2 = dpp_ror2(cur[bj][e]), p2 = dpp_ror2(pg[bj][e]);
;                             x1[e] = fr >= 1 ? c1 : p1; x2[e] = fr >= 2 ? c2 : p2; }
;                         h[bj] = bb[bj] + w0[bj] * x2 + w1[bj] * x1 + w2[bj] * cur[bj]; }
;                     if (ai == 0 && wr == 0 && m == 0 && fr < 2) {
;                         *(f32x4*)(hc0 + (size_t)(u.pm * 2 + fr) * FF2 + gcol + 4 * n) = h[0]; *(f32x4*)(hc0 + (size_t)(u.pm * 2 + fr) * FF2 + FF + gcol + 4 * n) = h[1]; }
;                     f32x4 a;
; #pragma unroll
;                     for (int e = 0; e < 4; ++e) { const float g = h[0][e]; a[e] = g * __builtin_amdgcn_rcpf(1.0f + __builtin_amdgcn_exp2f(-1.4426950408889634f * g)) * h[1][e]; }
;                     const unsigned p0 = cvt_pk_bf16(a[0], a[1]), p1 = cvt_pk_bf16(a[2], a[3]);
;                     if (n == 0) { pk_lo[ai][m][0] = p0; pk_lo[ai][m][1] = p1; }
	v_fmac_f32_dpp v250, v184, v146 row_shl:14 row_mask:0xf bank_mask:0xf
	v_fmac_f32_dpp v251, v185, v147 row_shl:14 row_mask:0xf bank_mask:0xf
	v_pk_mul_f32 v[224:225], v[220:221], s[100:101] op_sel_hi:[1,0]
	v_pk_mul_f32 v[190:191], v[222:223], s[100:101] op_sel_hi:[1,0]
	v_exp_f32_e32 v224, v224
	v_exp_f32_e32 v225, v225
	v_exp_f32_e32 v190, v190
	v_exp_f32_e32 v191, v191
	v_pk_mul_f32 v[220:221], v[220:221], v[248:249]
	v_pk_mul_f32 v[222:223], v[222:223], v[250:251]
	v_pk_add_f32 v[224:225], v[224:225], 1.0 op_sel_hi:[1,0]
	v_pk_add_f32 v[190:191], v[190:191], 1.0 op_sel_hi:[1,0]
	v_rcp_f32_e32 v224, v224
	v_rcp_f32_e32 v225, v225
	v_rcp_f32_e32 v190, v190
	v_rcp_f32_e32 v191, v191
	v_pk_mul_f32 v[220:221], v[220:221], v[224:225]
	v_pk_mul_f32 v[222:223], v[222:223], v[190:191]
	v_cvt_pk_bf16_f32 v160, v220, v221
	v_cvt_pk_bf16_f32 v161, v222, v223
	v_pk_mul_f32 v[84:85], v[84:85], v[236:237] op_sel_hi:[1,0]
	v_pk_mul_f32 v[86:87], v[86:87], v[236:237] op_sel_hi:[1,0]
	v_pk_mul_f32 v[80:81], v[80:81], v[236:237] op_sel_hi:[1,0]
	v_pk_mul_f32 v[82:83], v[82:83], v[236:237] op_sel_hi:[1,0]
	v_pk_fma_f32 v[220:221], v[136:137], v[84:85], v[140:141]
	v_pk_fma_f32 v[222:223], v[138:139], v[86:87], v[142:143]
	v_pk_fma_f32 v[248:249], v[152:153], v[80:81], v[156:157]
	v_pk_fma_f32 v[250:251], v[154:155], v[82:83], v[158:159]
	v_fmac_f32_dpp v220, v84, v132 row_shr:1 row_mask:0xf bank_mask:0xf
	v_fmac_f32_dpp v221, v85, v133 row_shr:1 row_mask:0xf bank_mask:0xf
	v_fmac_f32_dpp v222, v86, v134 row_shr:1 row_mask:0xf bank_mask:0xf
	v_fmac_f32_dpp v223, v87, v135 row_shr:1 row_mask:0xf bank_mask:0xf
	v_fmac_f32_dpp v248, v80, v148 row_shr:1 row_mask:0xf bank_mask:0xf
	v_fmac_f32_dpp v249, v81, v149 row_shr:1 row_mask:0xf bank_mask:0xf
	v_fmac_f32_dpp v250, v82, v150 row_shr:1 row_mask:0xf bank_mask:0xf
	v_fmac_f32_dpp v251, v83, v151 row_shr:1 row_mask:0xf bank_mask:0xf
	v_fmac_f32_dpp v220, v92, v132 row_shl:15 row_mask:0xf bank_mask:0xf
	v_fmac_f32_dpp v221, v93, v133 row_shl:15 row_mask:0xf bank_mask:0xf
	v_fmac_f32_dpp v222, v94, v134 row_shl:15 row_mask:0xf bank_mask:0xf
	v_fmac_f32_dpp v223, v95, v135 row_shl:15 row_mask:0xf bank_mask:0xf
	v_fmac_f32_dpp v248, v88, v148 row_shl:15 row_mask:0xf bank_mask:0xf
	v_fmac_f32_dpp v249, v89, v149 row_shl:15 row_mask:0xf bank_mask:0xf
	v_fmac_f32_dpp v250, v90, v150 row_shl:15 row_mask:0xf bank_mask:0xf
	v_fmac_f32_dpp v251, v91, v151 row_shl:15 row_mask:0xf bank_mask:0xf
	v_fmac_f32_dpp v220, v84, v128 row_shr:2 row_mask:0xf bank_mask:0xf
	v_fmac_f32_dpp v221, v85, v129 row_shr:2 row_mask:0xf bank_mask:0xf
	v_fmac_f32_dpp v222, v86, v130 row_shr:2 row_mask:0xf bank_mask:0xf
	v_fmac_f32_dpp v223, v87, v131 row_shr:2 row_mask:0xf bank_mask:0xf
	v_fmac_f32_dpp v248, v80, v144 row_shr:2 row_mask:0xf bank_mask:0xf
	v_fmac_f32_dpp v249, v81, v145 row_shr:2 row_mask:0xf bank_mask:0xf
	v_fmac_f32_dpp v250, v82, v146 row_shr:2 row_mask:0xf bank_mask:0xf
	v_fmac_f32_dpp v251, v83, v147 row_shr:2 row_mask:0xf bank_mask:0xf
	v_fmac_f32_dpp v220, v92, v128 row_shl:14 row_mask:0xf bank_mask:0xf
	v_fmac_f32_dpp v221, v93, v129 row_shl:14 row_mask:0xf bank_mask:0xf
	v_fmac_f32_dpp v222, v94, v130 row_shl:14 row_mask:0xf bank_mask:0xf
	v_fmac_f32_dpp v223, v95, v131 row_shl:14 row_mask:0xf bank_mask:0xf
	v_fmac_f32_dpp v248, v88, v144 row_shl:14 row_mask:0xf bank_mask:0xf
	v_fmac_f32_dpp v249, v89, v145 row_shl:14 row_mask:0xf bank_mask:0xf
	v_fmac_f32_dpp v250, v90, v146 row_shl:14 row_mask:0xf bank_mask:0xf
	v_fmac_f32_dpp v251, v91, v147 row_shl:14 row_mask:0xf bank_mask:0xf
	v_pk_mul_f32 v[224:225], v[220:221], s[100:101] op_sel_hi:[1,0]
	v_pk_mul_f32 v[190:191], v[222:223], s[100:101] op_sel_hi:[1,0]
	v_exp_f32_e32 v224, v224
	v_exp_f32_e32 v225, v225
	v_exp_f32_e32 v190, v190
	v_exp_f32_e32 v191, v191
	v_pk_mul_f32 v[220:221], v[220:221], v[248:249]
	v_pk_mul_f32 v[222:223], v[222:223], v[250:251]
	v_pk_add_f32 v[224:225], v[224:225], 1.0 op_sel_hi:[1,0]
	v_pk_add_f32 v[190:191], v[190:191], 1.0 op_sel_hi:[1,0]
	v_rcp_f32_e32 v224, v224
	v_rcp_f32_e32 v225, v225
	v_rcp_f32_e32 v190, v190
	v_rcp_f32_e32 v191, v191
	v_pk_mul_f32 v[220:221], v[220:221], v[224:225]
	v_pk_mul_f32 v[222:223], v[222:223], v[190:191]
	v_cvt_pk_bf16_f32 v164, v220, v221
	v_cvt_pk_bf16_f32 v165, v222, v223
	v_pk_mul_f32 v[76:77], v[76:77], v[238:239] op_sel_hi:[1,0]
	v_pk_mul_f32 v[78:79], v[78:79], v[238:239] op_sel_hi:[1,0]
	v_pk_mul_f32 v[72:73], v[72:73], v[238:239] op_sel_hi:[1,0]
	v_pk_mul_f32 v[74:75], v[74:75], v[238:239] op_sel_hi:[1,0]
	v_pk_fma_f32 v[220:221], v[136:137], v[76:77], v[140:141]
	v_pk_fma_f32 v[222:223], v[138:139], v[78:79], v[142:143]
	v_pk_fma_f32 v[248:249], v[152:153], v[72:73], v[156:157]
	v_pk_fma_f32 v[250:251], v[154:155], v[74:75], v[158:159]
	v_fmac_f32_dpp v220, v76, v132 row_shr:1 row_mask:0xf bank_mask:0xf
	v_fmac_f32_dpp v221, v77, v133 row_shr:1 row_mask:0xf bank_mask:0xf
	v_fmac_f32_dpp v222, v78, v134 row_shr:1 row_mask:0xf bank_mask:0xf
	v_fmac_f32_dpp v223, v79, v135 row_shr:1 row_mask:0xf bank_mask:0xf
	v_fmac_f32_dpp v248, v72, v148 row_shr:1 row_mask:0xf bank_mask:0xf
	v_fmac_f32_dpp v249, v73, v149 row_shr:1 row_mask:0xf bank_mask:0xf
	v_fmac_f32_dpp v250, v74, v150 row_shr:1 row_mask:0xf bank_mask:0xf
	v_fmac_f32_dpp v251, v75, v151 row_shr:1 row_mask:0xf bank_mask:0xf
	v_fmac_f32_dpp v220, v84, v132 row_shl:15 row_mask:0xf bank_mask:0xf
	v_fmac_f32_dpp v221, v85, v133 row_shl:15 row_mask:0xf bank_mask:0xf
	v_fmac_f32_dpp v222, v86, v134 row_shl:15 row_mask:0xf bank_mask:0xf
	v_fmac_f32_dpp v223, v87, v135 row_shl:15 row_mask:0xf bank_mask:0xf
	v_fmac_f32_dpp v248, v80, v148 row_shl:15 row_mask:0xf bank_mask:0xf
; #define PG8_LAS __attribute__((address_space(3)))
; __device__ __forceinline__ unsigned cvt_pk_bf16(float lo, float hi) { unsigned r; asm volatile("v_cvt_pk_bf16_f32 %0, %1, %2" : "=v"(r) : "v"(lo), "v"(hi)); return r; }
; __device__ __forceinline__ float dpp_ror1(float x) { return __int_as_float(__builtin_amdgcn_update_dpp(0, __float_as_int(x), 0x121, 0xf, 0xf, false)); }
; __device__ __forceinline__ float dpp_ror2(float x) { return __int_as_float(__builtin_amdgcn_update_dpp(0, __float_as_int(x), 0x122, 0xf, 0xf, false)); }
;     __device__ __forceinline__ void operator()(const f32x4 (&acc)[2][2][4][2], const Unit& u, int wr, int wc, int fr, int fq) const {
;     ...
;             for (int ai = 0; ai < 2; ++ai) {
;                 f32x4 pg[2]; const int pb = ai * 2 + wr - 1;
; #pragma unroll
;                 for (int bj = 0; bj < 2; ++bj) { pg[bj] = (f32x4){0.f, 0.f, 0.f, 0.f};
;                     if (pb >= 0 && fr >= 14) pg[bj] = *(const PG8_LAS f32x4*)(halo + (pb * 2 + (fr - 14)) * 256 + bj * HALF + lcol + 4 * n); }
; #pragma unroll
;                 for (int m = 0; m < 4; ++m) {
;                     f32x4 cur[2], h[2];
; #pragma unroll
;                     for (int bj = 0; bj < 2; ++bj) { cur[bj] = acc[ai][bj][m][n] * rs[ai][m]; f32x4 x1, x2;
; #pragma unroll
;                         for (int e = 0; e < 4; ++e) { const float c1 = dpp_ror1(cur[bj][e]), p1 = dpp_ror1(pg[bj][e]), c2 = dpp_ror2(cur[bj][e]), p2 = dpp_ror2(pg[bj][e]);
;                             x1[e] = fr >= 1 ? c1 : p1; x2[e] = fr >= 2 ? c2 : p2; }
;                         h[bj] = bb[bj] + w0[bj] * x2 + w1[bj] * x1 + w2[bj] * cur[bj]; }
;                     if (ai == 0 && wr == 0 && m == 0 && fr < 2) {
;                         *(f32x4*)(hc0 + (size_t)(u.pm * 2 + fr) * FF2 + gcol + 4 * n) = h[0]; *(f32x4*)(hc0 + (size_t)(u.pm * 2 + fr) * FF2 + FF + gcol + 4 * n) = h[1]; }
;                     f32x4 a;
; #pragma unroll
;                     for (int e = 0; e < 4; ++e) { const float g = h[0][e]; a[e] = g * __builtin_amdgcn_rcpf(1.0f + __builtin_amdgcn_exp2f(-1.4426950408889634f * g)) * h[1][e]; }
;                     const unsigned p0 = cvt_pk_bf16(a[0], a[1]), p1 = cvt_pk_bf16(a[2], a[3]);
;                     if (n == 0) { pk_lo[ai][m][0] = p0; pk_lo[ai][m][1] = p1; }
	v_fmac_f32_dpp v249, v81, v149 row_shl:15 row_mask:0xf bank_mask:0xf
	v_fmac_f32_dpp v250, v82, v150 row_shl:15 row_mask:0xf bank_mask:0xf
	v_fmac_f32_dpp v251, v83, v151 row_shl:15 row_mask:0xf bank_mask:0xf
	v_fmac_f32_dpp v220, v76, v128 row_shr:2 row_mask:0xf bank_mask:0xf
	v_fmac_f32_dpp v221, v77, v129 row_shr:2 row_mask:0xf bank_mask:0xf
	v_fmac_f32_dpp v222, v78, v130 row_shr:2 row_mask:0xf bank_mask:0xf
	v_fmac_f32_dpp v223, v79, v131 row_shr:2 row_mask:0xf bank_mask:0xf
	v_fmac_f32_dpp v248, v72, v144 row_shr:2 row_mask:0xf bank_mask:0xf
	v_fmac_f32_dpp v249, v73, v145 row_shr:2 row_mask:0xf bank_mask:0xf
	v_fmac_f32_dpp v250, v74, v146 row_shr:2 row_mask:0xf bank_mask:0xf
	v_fmac_f32_dpp v251, v75, v147 row_shr:2 row_mask:0xf bank_mask:0xf
	v_fmac_f32_dpp v220, v84, v128 row_shl:14 row_mask:0xf bank_mask:0xf
	v_fmac_f32_dpp v221, v85, v129 row_shl:14 row_mask:0xf bank_mask:0xf
	v_fmac_f32_dpp v222, v86, v130 row_shl:14 row_mask:0xf bank_mask:0xf
	v_fmac_f32_dpp v223, v87, v131 row_shl:14 row_mask:0xf bank_mask:0xf
	v_fmac_f32_dpp v248, v80, v144 row_shl:14 row_mask:0xf bank_mask:0xf
	v_fmac_f32_dpp v249, v81, v145 row_shl:14 row_mask:0xf bank_mask:0xf
	v_fmac_f32_dpp v250, v82, v146 row_shl:14 row_mask:0xf bank_mask:0xf
	v_fmac_f32_dpp v251, v83, v147 row_shl:14 row_mask:0xf bank_mask:0xf
	v_pk_mul_f32 v[224:225], v[220:221], s[100:101] op_sel_hi:[1,0]
	v_pk_mul_f32 v[190:191], v[222:223], s[100:101] op_sel_hi:[1,0]
	v_exp_f32_e32 v224, v224
	v_exp_f32_e32 v225, v225
	v_exp_f32_e32 v190, v190
	v_exp_f32_e32 v191, v191
	v_pk_mul_f32 v[220:221], v[220:221], v[248:249]
	v_pk_mul_f32 v[222:223], v[222:223], v[250:251]
	v_pk_add_f32 v[224:225], v[224:225], 1.0 op_sel_hi:[1,0]
	v_pk_add_f32 v[190:191], v[190:191], 1.0 op_sel_hi:[1,0]
	v_rcp_f32_e32 v224, v224
	v_rcp_f32_e32 v225, v225
	v_rcp_f32_e32 v190, v190
	v_rcp_f32_e32 v191, v191
	v_pk_mul_f32 v[220:221], v[220:221], v[224:225]
	v_pk_mul_f32 v[222:223], v[222:223], v[190:191]
	v_cvt_pk_bf16_f32 v178, v220, v221
	v_cvt_pk_bf16_f32 v179, v222, v223
	s_and_b64 vcc, exec, s[94:95]
	s_cbranch_vccnz .Lp7_hz1
	ds_read_b128 v[92:95], v215
	ds_read_b128 v[88:91], v216
	s_branch .Lp7_hr1
.Lp7_hz1:
	v_mov_b32_e32 v92, 0
	v_mov_b32_e32 v93, 0
	v_mov_b32_e32 v94, 0
	v_mov_b32_e32 v95, 0
	v_mov_b32_e32 v88, 0
	v_mov_b32_e32 v89, 0
	v_mov_b32_e32 v90, 0
	v_mov_b32_e32 v91, 0
.Lp7_hr1:
	ds_read_b128 v[84:87], v217
	ds_read_b128 v[80:83], v218
	v_pk_fma_f32 v[220:221], v[136:137], v[68:69], v[140:141]
	v_pk_fma_f32 v[222:223], v[138:139], v[70:71], v[142:143]
	v_pk_fma_f32 v[248:249], v[152:153], v[64:65], v[156:157]
	v_pk_fma_f32 v[250:251], v[154:155], v[66:67], v[158:159]
	v_fmac_f32_dpp v220, v68, v132 row_shr:1 row_mask:0xf bank_mask:0xf
	v_fmac_f32_dpp v221, v69, v133 row_shr:1 row_mask:0xf bank_mask:0xf
	v_fmac_f32_dpp v222, v70, v134 row_shr:1 row_mask:0xf bank_mask:0xf
	v_fmac_f32_dpp v223, v71, v135 row_shr:1 row_mask:0xf bank_mask:0xf
	v_fmac_f32_dpp v248, v64, v148 row_shr:1 row_mask:0xf bank_mask:0xf
	v_fmac_f32_dpp v249, v65, v149 row_shr:1 row_mask:0xf bank_mask:0xf
	v_fmac_f32_dpp v250, v66, v150 row_shr:1 row_mask:0xf bank_mask:0xf
	v_fmac_f32_dpp v251, v67, v151 row_shr:1 row_mask:0xf bank_mask:0xf
	v_fmac_f32_dpp v220, v76, v132 row_shl:15 row_mask:0xf bank_mask:0xf
	v_fmac_f32_dpp v221, v77, v133 row_shl:15 row_mask:0xf bank_mask:0xf
	v_fmac_f32_dpp v222, v78, v134 row_shl:15 row_mask:0xf bank_mask:0xf
	v_fmac_f32_dpp v223, v79, v135 row_shl:15 row_mask:0xf bank_mask:0xf
	v_fmac_f32_dpp v248, v72, v148 row_shl:15 row_mask:0xf bank_mask:0xf
	v_fmac_f32_dpp v249, v73, v149 row_shl:15 row_mask:0xf bank_mask:0xf
	v_fmac_f32_dpp v250, v74, v150 row_shl:15 row_mask:0xf bank_mask:0xf
	v_fmac_f32_dpp v251, v75, v151 row_shl:15 row_mask:0xf bank_mask:0xf
	v_fmac_f32_dpp v220, v68, v128 row_shr:2 row_mask:0xf bank_mask:0xf
	v_fmac_f32_dpp v221, v69, v129 row_shr:2 row_mask:0xf bank_mask:0xf
	v_fmac_f32_dpp v222, v70, v130 row_shr:2 row_mask:0xf bank_mask:0xf
	v_fmac_f32_dpp v223, v71, v131 row_shr:2 row_mask:0xf bank_mask:0xf
	v_fmac_f32_dpp v248, v64, v144 row_shr:2 row_mask:0xf bank_mask:0xf
	v_fmac_f32_dpp v249, v65, v145 row_shr:2 row_mask:0xf bank_mask:0xf
	v_fmac_f32_dpp v250, v66, v146 row_shr:2 row_mask:0xf bank_mask:0xf
	v_fmac_f32_dpp v251, v67, v147 row_shr:2 row_mask:0xf bank_mask:0xf
	v_fmac_f32_dpp v220, v76, v128 row_shl:14 row_mask:0xf bank_mask:0xf
	v_fmac_f32_dpp v221, v77, v129 row_shl:14 row_mask:0xf bank_mask:0xf
	v_fmac_f32_dpp v222, v78, v130 row_shl:14 row_mask:0xf bank_mask:0xf
	v_fmac_f32_dpp v223, v79, v131 row_shl:14 row_mask:0xf bank_mask:0xf
	v_fmac_f32_dpp v248, v72, v144 row_shl:14 row_mask:0xf bank_mask:0xf
	v_fmac_f32_dpp v249, v73, v145 row_shl:14 row_mask:0xf bank_mask:0xf
	v_fmac_f32_dpp v250, v74, v146 row_shl:14 row_mask:0xf bank_mask:0xf
	v_fmac_f32_dpp v251, v75, v147 row_shl:14 row_mask:0xf bank_mask:0xf
	v_pk_mul_f32 v[224:225], v[220:221], s[100:101] op_sel_hi:[1,0]
	v_pk_mul_f32 v[190:191], v[222:223], s[100:101] op_sel_hi:[1,0]
	v_exp_f32_e32 v224, v224
	v_exp_f32_e32 v225, v225
	v_exp_f32_e32 v190, v190
	v_exp_f32_e32 v191, v191
	v_pk_mul_f32 v[220:221], v[220:221], v[248:249]
	v_pk_mul_f32 v[222:223], v[222:223], v[250:251]
	v_pk_add_f32 v[224:225], v[224:225], 1.0 op_sel_hi:[1,0]
	v_pk_add_f32 v[190:191], v[190:191], 1.0 op_sel_hi:[1,0]
	v_rcp_f32_e32 v224, v224
	v_rcp_f32_e32 v225, v225
	v_rcp_f32_e32 v190, v190
	v_rcp_f32_e32 v191, v191
	v_pk_mul_f32 v[220:221], v[220:221], v[224:225]
	v_pk_mul_f32 v[222:223], v[222:223], v[190:191]
	v_cvt_pk_bf16_f32 v182, v220, v221
	v_cvt_pk_bf16_f32 v183, v222, v223
	s_waitcnt vmcnt(0) lgkmcnt(0)
; __device__ __forceinline__ unsigned cvt_pk_bf16(float lo, float hi) { unsigned r; asm volatile("v_cvt_pk_bf16_f32 %0, %1, %2" : "=v"(r) : "v"(lo), "v"(hi)); return r; }
; __device__ __forceinline__ float dpp_ror1(float x) { return __int_as_float(__builtin_amdgcn_update_dpp(0, __float_as_int(x), 0x121, 0xf, 0xf, false)); }
; __device__ __forceinline__ float dpp_ror2(float x) { return __int_as_float(__builtin_amdgcn_update_dpp(0, __float_as_int(x), 0x122, 0xf, 0xf, false)); }
;     __device__ __forceinline__ void operator()(const f32x4 (&acc)[2][2][4][2], const Unit& u, int wr, int wc, int fr, int fq) const {
;     ...
;                 for (int m = 0; m < 4; ++m) {
;                     f32x4 cur[2], h[2];
; #pragma unroll
;                     for (int bj = 0; bj < 2; ++bj) { cur[bj] = acc[ai][bj][m][n] * rs[ai][m]; f32x4 x1, x2;
; #pragma unroll
;                         for (int e = 0; e < 4; ++e) { const float c1 = dpp_ror1(cur[bj][e]), p1 = dpp_ror1(pg[bj][e]), c2 = dpp_ror2(cur[bj][e]), p2 = dpp_ror2(pg[bj][e]);
;                             x1[e] = fr >= 1 ? c1 : p1; x2[e] = fr >= 2 ? c2 : p2; }
;                         h[bj] = bb[bj] + w0[bj] * x2 + w1[bj] * x1 + w2[bj] * cur[bj]; }
;                     if (ai == 0 && wr == 0 && m == 0 && fr < 2) {
;                         *(f32x4*)(hc0 + (size_t)(u.pm * 2 + fr) * FF2 + gcol + 4 * n) = h[0]; *(f32x4*)(hc0 + (size_t)(u.pm * 2 + fr) * FF2 + FF + gcol + 4 * n) = h[1]; }
;                     f32x4 a;
; #pragma unroll
;                     for (int e = 0; e < 4; ++e) { const float g = h[0][e]; a[e] = g * __builtin_amdgcn_rcpf(1.0f + __builtin_amdgcn_exp2f(-1.4426950408889634f * g)) * h[1][e]; }
;                     const unsigned p0 = cvt_pk_bf16(a[0], a[1]), p1 = cvt_pk_bf16(a[2], a[3]);
;                     if (n == 0) { pk_lo[ai][m][0] = p0; pk_lo[ai][m][1] = p1; }
;                     else { u32x4 w; w.x = pk_lo[ai][m][0]; w.y = pk_lo[ai][m][1]; w.z = p0; w.w = p1;
;                         *(u32x4*)(act + (size_t)(u.pm * BM + ai * HALF + wr * 64 + m * 16 + fr) * FF + gcol) = w; }
;                     pg[0] = cur[0]; pg[1] = cur[1];
	v_pk_mul_f32 v[60:61], v[60:61], v[226:227] op_sel_hi:[1,0]
	v_pk_mul_f32 v[62:63], v[62:63], v[226:227] op_sel_hi:[1,0]
	v_pk_mul_f32 v[56:57], v[56:57], v[226:227] op_sel_hi:[1,0]
	v_pk_mul_f32 v[58:59], v[58:59], v[226:227] op_sel_hi:[1,0]
	v_pk_fma_f32 v[220:221], v[108:109], v[60:61], v[100:101]
	v_pk_fma_f32 v[222:223], v[110:111], v[62:63], v[102:103]
	v_pk_fma_f32 v[248:249], v[104:105], v[56:57], v[96:97]
	v_pk_fma_f32 v[250:251], v[106:107], v[58:59], v[98:99]
	v_fmac_f32_dpp v220, v60, v116 row_shr:1 row_mask:0xf bank_mask:0xf
	v_fmac_f32_dpp v221, v61, v117 row_shr:1 row_mask:0xf bank_mask:0xf
	v_fmac_f32_dpp v222, v62, v118 row_shr:1 row_mask:0xf bank_mask:0xf
	v_fmac_f32_dpp v223, v63, v119 row_shr:1 row_mask:0xf bank_mask:0xf
	v_fmac_f32_dpp v248, v56, v112 row_shr:1 row_mask:0xf bank_mask:0xf
	v_fmac_f32_dpp v249, v57, v113 row_shr:1 row_mask:0xf bank_mask:0xf
	v_fmac_f32_dpp v250, v58, v114 row_shr:1 row_mask:0xf bank_mask:0xf
	v_fmac_f32_dpp v251, v59, v115 row_shr:1 row_mask:0xf bank_mask:0xf
	v_fmac_f32_dpp v220, v92, v116 row_shl:15 row_mask:0xf bank_mask:0xf
	v_fmac_f32_dpp v221, v93, v117 row_shl:15 row_mask:0xf bank_mask:0xf
	v_fmac_f32_dpp v222, v94, v118 row_shl:15 row_mask:0xf bank_mask:0xf
	v_fmac_f32_dpp v223, v95, v119 row_shl:15 row_mask:0xf bank_mask:0xf
	v_fmac_f32_dpp v248, v88, v112 row_shl:15 row_mask:0xf bank_mask:0xf
	v_fmac_f32_dpp v249, v89, v113 row_shl:15 row_mask:0xf bank_mask:0xf
	v_fmac_f32_dpp v250, v90, v114 row_shl:15 row_mask:0xf bank_mask:0xf
	v_fmac_f32_dpp v251, v91, v115 row_shl:15 row_mask:0xf bank_mask:0xf
	v_fmac_f32_dpp v220, v60, v124 row_shr:2 row_mask:0xf bank_mask:0xf
	v_fmac_f32_dpp v221, v61, v125 row_shr:2 row_mask:0xf bank_mask:0xf
	v_fmac_f32_dpp v222, v62, v126 row_shr:2 row_mask:0xf bank_mask:0xf
	v_fmac_f32_dpp v223, v63, v127 row_shr:2 row_mask:0xf bank_mask:0xf
	v_fmac_f32_dpp v248, v56, v120 row_shr:2 row_mask:0xf bank_mask:0xf
	v_fmac_f32_dpp v249, v57, v121 row_shr:2 row_mask:0xf bank_mask:0xf
	v_fmac_f32_dpp v250, v58, v122 row_shr:2 row_mask:0xf bank_mask:0xf
	v_fmac_f32_dpp v251, v59, v123 row_shr:2 row_mask:0xf bank_mask:0xf
	v_fmac_f32_dpp v220, v92, v124 row_shl:14 row_mask:0xf bank_mask:0xf
	v_fmac_f32_dpp v221, v93, v125 row_shl:14 row_mask:0xf bank_mask:0xf
	v_fmac_f32_dpp v222, v94, v126 row_shl:14 row_mask:0xf bank_mask:0xf
	v_fmac_f32_dpp v223, v95, v127 row_shl:14 row_mask:0xf bank_mask:0xf
	v_fmac_f32_dpp v248, v88, v120 row_shl:14 row_mask:0xf bank_mask:0xf
	v_fmac_f32_dpp v249, v89, v121 row_shl:14 row_mask:0xf bank_mask:0xf
	v_fmac_f32_dpp v250, v90, v122 row_shl:14 row_mask:0xf bank_mask:0xf
	v_fmac_f32_dpp v251, v91, v123 row_shl:14 row_mask:0xf bank_mask:0xf
	s_and_saveexec_b64 s[0:1], s[12:13]
	global_store_dwordx4 v239, v[220:223], s[84:85] offset:16
	global_store_dwordx4 v241, v[248:251], s[84:85] offset:16
	s_or_b64 exec, exec, s[0:1]
	v_pk_mul_f32 v[224:225], v[220:221], s[100:101] op_sel_hi:[1,0]
	v_pk_mul_f32 v[190:191], v[222:223], s[100:101] op_sel_hi:[1,0]
	v_exp_f32_e32 v224, v224
	v_exp_f32_e32 v225, v225
	v_exp_f32_e32 v190, v190
	v_exp_f32_e32 v191, v191
	v_pk_mul_f32 v[220:221], v[220:221], v[248:249]
	v_pk_mul_f32 v[222:223], v[222:223], v[250:251]
	v_pk_add_f32 v[224:225], v[224:225], 1.0 op_sel_hi:[1,0]
	v_pk_add_f32 v[190:191], v[190:191], 1.0 op_sel_hi:[1,0]
	v_rcp_f32_e32 v224, v224
	v_rcp_f32_e32 v225, v225
	v_rcp_f32_e32 v190, v190
	v_rcp_f32_e32 v191, v191
	v_pk_mul_f32 v[220:221], v[220:221], v[224:225]
	v_pk_mul_f32 v[222:223], v[222:223], v[190:191]
	v_cvt_pk_bf16_f32 v188, v220, v221
	v_cvt_pk_bf16_f32 v189, v222, v223
	global_store_dwordx4 v237, v[186:189], s[24:25]
	v_pk_mul_f32 v[52:53], v[52:53], v[228:229] op_sel_hi:[1,0]
	v_pk_mul_f32 v[54:55], v[54:55], v[228:229] op_sel_hi:[1,0]
	v_pk_mul_f32 v[48:49], v[48:49], v[228:229] op_sel_hi:[1,0]
	v_pk_mul_f32 v[50:51], v[50:51], v[228:229] op_sel_hi:[1,0]
	v_pk_fma_f32 v[220:221], v[108:109], v[52:53], v[100:101]
	v_pk_fma_f32 v[222:223], v[110:111], v[54:55], v[102:103]
	v_pk_fma_f32 v[248:249], v[104:105], v[48:49], v[96:97]
	v_pk_fma_f32 v[250:251], v[106:107], v[50:51], v[98:99]
	v_fmac_f32_dpp v220, v52, v116 row_shr:1 row_mask:0xf bank_mask:0xf
	v_fmac_f32_dpp v221, v53, v117 row_shr:1 row_mask:0xf bank_mask:0xf
	v_fmac_f32_dpp v222, v54, v118 row_shr:1 row_mask:0xf bank_mask:0xf
	v_fmac_f32_dpp v223, v55, v119 row_shr:1 row_mask:0xf bank_mask:0xf
	v_fmac_f32_dpp v248, v48, v112 row_shr:1 row_mask:0xf bank_mask:0xf
	v_fmac_f32_dpp v249, v49, v113 row_shr:1 row_mask:0xf bank_mask:0xf
	v_fmac_f32_dpp v250, v50, v114 row_shr:1 row_mask:0xf bank_mask:0xf
	v_fmac_f32_dpp v251, v51, v115 row_shr:1 row_mask:0xf bank_mask:0xf
	v_fmac_f32_dpp v220, v60, v116 row_shl:15 row_mask:0xf bank_mask:0xf
	v_fmac_f32_dpp v221, v61, v117 row_shl:15 row_mask:0xf bank_mask:0xf
	v_fmac_f32_dpp v222, v62, v118 row_shl:15 row_mask:0xf bank_mask:0xf
	v_fmac_f32_dpp v223, v63, v119 row_shl:15 row_mask:0xf bank_mask:0xf
	v_fmac_f32_dpp v248, v56, v112 row_shl:15 row_mask:0xf bank_mask:0xf
	v_fmac_f32_dpp v249, v57, v113 row_shl:15 row_mask:0xf bank_mask:0xf
	v_fmac_f32_dpp v250, v58, v114 row_shl:15 row_mask:0xf bank_mask:0xf
	v_fmac_f32_dpp v251, v59, v115 row_shl:15 row_mask:0xf bank_mask:0xf
	v_fmac_f32_dpp v220, v52, v124 row_shr:2 row_mask:0xf bank_mask:0xf
	v_fmac_f32_dpp v221, v53, v125 row_shr:2 row_mask:0xf bank_mask:0xf
	v_fmac_f32_dpp v222, v54, v126 row_shr:2 row_mask:0xf bank_mask:0xf
	v_fmac_f32_dpp v223, v55, v127 row_shr:2 row_mask:0xf bank_mask:0xf
	v_fmac_f32_dpp v248, v48, v120 row_shr:2 row_mask:0xf bank_mask:0xf
	v_fmac_f32_dpp v249, v49, v121 row_shr:2 row_mask:0xf bank_mask:0xf
; __device__ __forceinline__ unsigned cvt_pk_bf16(float lo, float hi) { unsigned r; asm volatile("v_cvt_pk_bf16_f32 %0, %1, %2" : "=v"(r) : "v"(lo), "v"(hi)); return r; }
; __device__ __forceinline__ float dpp_ror1(float x) { return __int_as_float(__builtin_amdgcn_update_dpp(0, __float_as_int(x), 0x121, 0xf, 0xf, false)); }
; __device__ __forceinline__ float dpp_ror2(float x) { return __int_as_float(__builtin_amdgcn_update_dpp(0, __float_as_int(x), 0x122, 0xf, 0xf, false)); }
;     __device__ __forceinline__ void operator()(const f32x4 (&acc)[2][2][4][2], const Unit& u, int wr, int wc, int fr, int fq) const {
;     ...
;                 for (int m = 0; m < 4; ++m) {
;                     f32x4 cur[2], h[2];
; #pragma unroll
;                     for (int bj = 0; bj < 2; ++bj) { cur[bj] = acc[ai][bj][m][n] * rs[ai][m]; f32x4 x1, x2;
; #pragma unroll
;                         for (int e = 0; e < 4; ++e) { const float c1 = dpp_ror1(cur[bj][e]), p1 = dpp_ror1(pg[bj][e]), c2 = dpp_ror2(cur[bj][e]), p2 = dpp_ror2(pg[bj][e]);
;                             x1[e] = fr >= 1 ? c1 : p1; x2[e] = fr >= 2 ? c2 : p2; }
;                         h[bj] = bb[bj] + w0[bj] * x2 + w1[bj] * x1 + w2[bj] * cur[bj]; }
;                     if (ai == 0 && wr == 0 && m == 0 && fr < 2) {
;                         *(f32x4*)(hc0 + (size_t)(u.pm * 2 + fr) * FF2 + gcol + 4 * n) = h[0]; *(f32x4*)(hc0 + (size_t)(u.pm * 2 + fr) * FF2 + FF + gcol + 4 * n) = h[1]; }
;                     f32x4 a;
; #pragma unroll
;                     for (int e = 0; e < 4; ++e) { const float g = h[0][e]; a[e] = g * __builtin_amdgcn_rcpf(1.0f + __builtin_amdgcn_exp2f(-1.4426950408889634f * g)) * h[1][e]; }
;                     const unsigned p0 = cvt_pk_bf16(a[0], a[1]), p1 = cvt_pk_bf16(a[2], a[3]);
;                     if (n == 0) { pk_lo[ai][m][0] = p0; pk_lo[ai][m][1] = p1; }
;                     else { u32x4 w; w.x = pk_lo[ai][m][0]; w.y = pk_lo[ai][m][1]; w.z = p0; w.w = p1;
;                         *(u32x4*)(act + (size_t)(u.pm * BM + ai * HALF + wr * 64 + m * 16 + fr) * FF + gcol) = w; }
;                     pg[0] = cur[0]; pg[1] = cur[1];
	v_fmac_f32_dpp v250, v50, v122 row_shr:2 row_mask:0xf bank_mask:0xf
	v_fmac_f32_dpp v251, v51, v123 row_shr:2 row_mask:0xf bank_mask:0xf
	v_fmac_f32_dpp v220, v60, v124 row_shl:14 row_mask:0xf bank_mask:0xf
	v_fmac_f32_dpp v221, v61, v125 row_shl:14 row_mask:0xf bank_mask:0xf
	v_fmac_f32_dpp v222, v62, v126 row_shl:14 row_mask:0xf bank_mask:0xf
	v_fmac_f32_dpp v223, v63, v127 row_shl:14 row_mask:0xf bank_mask:0xf
	v_fmac_f32_dpp v248, v56, v120 row_shl:14 row_mask:0xf bank_mask:0xf
	v_fmac_f32_dpp v249, v57, v121 row_shl:14 row_mask:0xf bank_mask:0xf
	v_fmac_f32_dpp v250, v58, v122 row_shl:14 row_mask:0xf bank_mask:0xf
	v_fmac_f32_dpp v251, v59, v123 row_shl:14 row_mask:0xf bank_mask:0xf
	v_pk_mul_f32 v[224:225], v[220:221], s[100:101] op_sel_hi:[1,0]
	v_pk_mul_f32 v[190:191], v[222:223], s[100:101] op_sel_hi:[1,0]
	v_exp_f32_e32 v224, v224
	v_exp_f32_e32 v225, v225
	v_exp_f32_e32 v190, v190
	v_exp_f32_e32 v191, v191
	v_pk_mul_f32 v[220:221], v[220:221], v[248:249]
	v_pk_mul_f32 v[222:223], v[222:223], v[250:251]
	v_pk_add_f32 v[224:225], v[224:225], 1.0 op_sel_hi:[1,0]
	v_pk_add_f32 v[190:191], v[190:191], 1.0 op_sel_hi:[1,0]
	v_rcp_f32_e32 v224, v224
	v_rcp_f32_e32 v225, v225
	v_rcp_f32_e32 v190, v190
	v_rcp_f32_e32 v191, v191
	v_pk_mul_f32 v[220:221], v[220:221], v[224:225]
	v_pk_mul_f32 v[222:223], v[222:223], v[190:191]
	v_cvt_pk_bf16_f32 v196, v220, v221
	v_cvt_pk_bf16_f32 v197, v222, v223
	v_add_u32_e32 v243, 0x16000, v237
	global_store_dwordx4 v243, v[194:197], s[24:25]
	v_pk_mul_f32 v[44:45], v[44:45], v[230:231] op_sel_hi:[1,0]
	v_pk_mul_f32 v[46:47], v[46:47], v[230:231] op_sel_hi:[1,0]
	v_pk_mul_f32 v[40:41], v[40:41], v[230:231] op_sel_hi:[1,0]
	v_pk_mul_f32 v[42:43], v[42:43], v[230:231] op_sel_hi:[1,0]
	v_pk_fma_f32 v[220:221], v[108:109], v[44:45], v[100:101]
	v_pk_fma_f32 v[222:223], v[110:111], v[46:47], v[102:103]
	v_pk_fma_f32 v[248:249], v[104:105], v[40:41], v[96:97]
	v_pk_fma_f32 v[250:251], v[106:107], v[42:43], v[98:99]
	v_fmac_f32_dpp v220, v44, v116 row_shr:1 row_mask:0xf bank_mask:0xf
	v_fmac_f32_dpp v221, v45, v117 row_shr:1 row_mask:0xf bank_mask:0xf
	v_fmac_f32_dpp v222, v46, v118 row_shr:1 row_mask:0xf bank_mask:0xf
	v_fmac_f32_dpp v223, v47, v119 row_shr:1 row_mask:0xf bank_mask:0xf
	v_fmac_f32_dpp v248, v40, v112 row_shr:1 row_mask:0xf bank_mask:0xf
	v_fmac_f32_dpp v249, v41, v113 row_shr:1 row_mask:0xf bank_mask:0xf
	v_fmac_f32_dpp v250, v42, v114 row_shr:1 row_mask:0xf bank_mask:0xf
	v_fmac_f32_dpp v251, v43, v115 row_shr:1 row_mask:0xf bank_mask:0xf
	v_fmac_f32_dpp v220, v52, v116 row_shl:15 row_mask:0xf bank_mask:0xf
	v_fmac_f32_dpp v221, v53, v117 row_shl:15 row_mask:0xf bank_mask:0xf
	v_fmac_f32_dpp v222, v54, v118 row_shl:15 row_mask:0xf bank_mask:0xf
	v_fmac_f32_dpp v223, v55, v119 row_shl:15 row_mask:0xf bank_mask:0xf
	v_fmac_f32_dpp v248, v48, v112 row_shl:15 row_mask:0xf bank_mask:0xf
	v_fmac_f32_dpp v249, v49, v113 row_shl:15 row_mask:0xf bank_mask:0xf
	v_fmac_f32_dpp v250, v50, v114 row_shl:15 row_mask:0xf bank_mask:0xf
	v_fmac_f32_dpp v251, v51, v115 row_shl:15 row_mask:0xf bank_mask:0xf
	v_fmac_f32_dpp v220, v44, v124 row_shr:2 row_mask:0xf bank_mask:0xf
	v_fmac_f32_dpp v221, v45, v125 row_shr:2 row_mask:0xf bank_mask:0xf
	v_fmac_f32_dpp v222, v46, v126 row_shr:2 row_mask:0xf bank_mask:0xf
	v_fmac_f32_dpp v223, v47, v127 row_shr:2 row_mask:0xf bank_mask:0xf
	v_fmac_f32_dpp v248, v40, v120 row_shr:2 row_mask:0xf bank_mask:0xf
	v_fmac_f32_dpp v249, v41, v121 row_shr:2 row_mask:0xf bank_mask:0xf
	v_fmac_f32_dpp v250, v42, v122 row_shr:2 row_mask:0xf bank_mask:0xf
	v_fmac_f32_dpp v251, v43, v123 row_shr:2 row_mask:0xf bank_mask:0xf
	v_fmac_f32_dpp v220, v52, v124 row_shl:14 row_mask:0xf bank_mask:0xf
	v_fmac_f32_dpp v221, v53, v125 row_shl:14 row_mask:0xf bank_mask:0xf
	v_fmac_f32_dpp v222, v54, v126 row_shl:14 row_mask:0xf bank_mask:0xf
	v_fmac_f32_dpp v223, v55, v127 row_shl:14 row_mask:0xf bank_mask:0xf
	v_fmac_f32_dpp v248, v48, v120 row_shl:14 row_mask:0xf bank_mask:0xf
	v_fmac_f32_dpp v249, v49, v121 row_shl:14 row_mask:0xf bank_mask:0xf
	v_fmac_f32_dpp v250, v50, v122 row_shl:14 row_mask:0xf bank_mask:0xf
	v_fmac_f32_dpp v251, v51, v123 row_shl:14 row_mask:0xf bank_mask:0xf
	v_pk_mul_f32 v[224:225], v[220:221], s[100:101] op_sel_hi:[1,0]
	v_pk_mul_f32 v[190:191], v[222:223], s[100:101] op_sel_hi:[1,0]
	v_exp_f32_e32 v224, v224
	v_exp_f32_e32 v225, v225
	v_exp_f32_e32 v190, v190
	v_exp_f32_e32 v191, v191
	v_pk_mul_f32 v[220:221], v[220:221], v[248:249]
	v_pk_mul_f32 v[222:223], v[222:223], v[250:251]
	v_pk_add_f32 v[224:225], v[224:225], 1.0 op_sel_hi:[1,0]
	v_pk_add_f32 v[190:191], v[190:191], 1.0 op_sel_hi:[1,0]
	v_rcp_f32_e32 v224, v224
	v_rcp_f32_e32 v225, v225
	v_rcp_f32_e32 v190, v190
	v_rcp_f32_e32 v191, v191
	v_pk_mul_f32 v[220:221], v[220:221], v[224:225]
	v_pk_mul_f32 v[222:223], v[222:223], v[190:191]
	v_cvt_pk_bf16_f32 v200, v220, v221
	v_cvt_pk_bf16_f32 v201, v222, v223
	v_add_u32_e32 v243, 0x2c000, v237
	global_store_dwordx4 v243, v[198:201], s[24:25]
	v_pk_fma_f32 v[220:221], v[108:109], v[36:37], v[100:101]
	v_pk_fma_f32 v[222:223], v[110:111], v[38:39], v[102:103]
	v_pk_fma_f32 v[248:249], v[104:105], v[32:33], v[96:97]
	v_pk_fma_f32 v[250:251], v[106:107], v[34:35], v[98:99]
	v_fmac_f32_dpp v220, v36, v116 row_shr:1 row_mask:0xf bank_mask:0xf
	v_fmac_f32_dpp v221, v37, v117 row_shr:1 row_mask:0xf bank_mask:0xf
	v_fmac_f32_dpp v222, v38, v118 row_shr:1 row_mask:0xf bank_mask:0xf
	v_fmac_f32_dpp v223, v39, v119 row_shr:1 row_mask:0xf bank_mask:0xf
	v_fmac_f32_dpp v248, v32, v112 row_shr:1 row_mask:0xf bank_mask:0xf
	v_fmac_f32_dpp v249, v33, v113 row_shr:1 row_mask:0xf bank_mask:0xf
; __device__ __forceinline__ unsigned cvt_pk_bf16(float lo, float hi) { unsigned r; asm volatile("v_cvt_pk_bf16_f32 %0, %1, %2" : "=v"(r) : "v"(lo), "v"(hi)); return r; }
; __device__ __forceinline__ float dpp_ror1(float x) { return __int_as_float(__builtin_amdgcn_update_dpp(0, __float_as_int(x), 0x121, 0xf, 0xf, false)); }
; __device__ __forceinline__ float dpp_ror2(float x) { return __int_as_float(__builtin_amdgcn_update_dpp(0, __float_as_int(x), 0x122, 0xf, 0xf, false)); }
;     __device__ __forceinline__ void operator()(const f32x4 (&acc)[2][2][4][2], const Unit& u, int wr, int wc, int fr, int fq) const {
;     ...
;                 for (int m = 0; m < 4; ++m) {
;                     f32x4 cur[2], h[2];
; #pragma unroll
;                     for (int bj = 0; bj < 2; ++bj) { cur[bj] = acc[ai][bj][m][n] * rs[ai][m]; f32x4 x1, x2;
; #pragma unroll
;                         for (int e = 0; e < 4; ++e) { const float c1 = dpp_ror1(cur[bj][e]), p1 = dpp_ror1(pg[bj][e]), c2 = dpp_ror2(cur[bj][e]), p2 = dpp_ror2(pg[bj][e]);
;                             x1[e] = fr >= 1 ? c1 : p1; x2[e] = fr >= 2 ? c2 : p2; }
;                         h[bj] = bb[bj] + w0[bj] * x2 + w1[bj] * x1 + w2[bj] * cur[bj]; }
;                     if (ai == 0 && wr == 0 && m == 0 && fr < 2) {
;                         *(f32x4*)(hc0 + (size_t)(u.pm * 2 + fr) * FF2 + gcol + 4 * n) = h[0]; *(f32x4*)(hc0 + (size_t)(u.pm * 2 + fr) * FF2 + FF + gcol + 4 * n) = h[1]; }
;                     f32x4 a;
; #pragma unroll
;                     for (int e = 0; e < 4; ++e) { const float g = h[0][e]; a[e] = g * __builtin_amdgcn_rcpf(1.0f + __builtin_amdgcn_exp2f(-1.4426950408889634f * g)) * h[1][e]; }
;                     const unsigned p0 = cvt_pk_bf16(a[0], a[1]), p1 = cvt_pk_bf16(a[2], a[3]);
;                     if (n == 0) { pk_lo[ai][m][0] = p0; pk_lo[ai][m][1] = p1; }
;                     else { u32x4 w; w.x = pk_lo[ai][m][0]; w.y = pk_lo[ai][m][1]; w.z = p0; w.w = p1;
;                         *(u32x4*)(act + (size_t)(u.pm * BM + ai * HALF + wr * 64 + m * 16 + fr) * FF + gcol) = w; }
;                     pg[0] = cur[0]; pg[1] = cur[1];
	v_fmac_f32_dpp v250, v34, v114 row_shr:1 row_mask:0xf bank_mask:0xf
	v_fmac_f32_dpp v251, v35, v115 row_shr:1 row_mask:0xf bank_mask:0xf
	v_fmac_f32_dpp v220, v44, v116 row_shl:15 row_mask:0xf bank_mask:0xf
	v_fmac_f32_dpp v221, v45, v117 row_shl:15 row_mask:0xf bank_mask:0xf
	v_fmac_f32_dpp v222, v46, v118 row_shl:15 row_mask:0xf bank_mask:0xf
	v_fmac_f32_dpp v223, v47, v119 row_shl:15 row_mask:0xf bank_mask:0xf
	v_fmac_f32_dpp v248, v40, v112 row_shl:15 row_mask:0xf bank_mask:0xf
	v_fmac_f32_dpp v249, v41, v113 row_shl:15 row_mask:0xf bank_mask:0xf
	v_fmac_f32_dpp v250, v42, v114 row_shl:15 row_mask:0xf bank_mask:0xf
	v_fmac_f32_dpp v251, v43, v115 row_shl:15 row_mask:0xf bank_mask:0xf
	v_fmac_f32_dpp v220, v36, v124 row_shr:2 row_mask:0xf bank_mask:0xf
	v_fmac_f32_dpp v221, v37, v125 row_shr:2 row_mask:0xf bank_mask:0xf
	v_fmac_f32_dpp v222, v38, v126 row_shr:2 row_mask:0xf bank_mask:0xf
	v_fmac_f32_dpp v223, v39, v127 row_shr:2 row_mask:0xf bank_mask:0xf
	v_fmac_f32_dpp v248, v32, v120 row_shr:2 row_mask:0xf bank_mask:0xf
	v_fmac_f32_dpp v249, v33, v121 row_shr:2 row_mask:0xf bank_mask:0xf
	v_fmac_f32_dpp v250, v34, v122 row_shr:2 row_mask:0xf bank_mask:0xf
	v_fmac_f32_dpp v251, v35, v123 row_shr:2 row_mask:0xf bank_mask:0xf
	v_fmac_f32_dpp v220, v44, v124 row_shl:14 row_mask:0xf bank_mask:0xf
	v_fmac_f32_dpp v221, v45, v125 row_shl:14 row_mask:0xf bank_mask:0xf
	v_fmac_f32_dpp v222, v46, v126 row_shl:14 row_mask:0xf bank_mask:0xf
	v_fmac_f32_dpp v223, v47, v127 row_shl:14 row_mask:0xf bank_mask:0xf
	v_fmac_f32_dpp v248, v40, v120 row_shl:14 row_mask:0xf bank_mask:0xf
	v_fmac_f32_dpp v249, v41, v121 row_shl:14 row_mask:0xf bank_mask:0xf
	v_fmac_f32_dpp v250, v42, v122 row_shl:14 row_mask:0xf bank_mask:0xf
	v_fmac_f32_dpp v251, v43, v123 row_shl:14 row_mask:0xf bank_mask:0xf
	v_pk_mul_f32 v[224:225], v[220:221], s[100:101] op_sel_hi:[1,0]
	v_pk_mul_f32 v[190:191], v[222:223], s[100:101] op_sel_hi:[1,0]
	v_exp_f32_e32 v224, v224
	v_exp_f32_e32 v225, v225
	v_exp_f32_e32 v190, v190
	v_exp_f32_e32 v191, v191
	v_pk_mul_f32 v[220:221], v[220:221], v[248:249]
	v_pk_mul_f32 v[222:223], v[222:223], v[250:251]
	v_pk_add_f32 v[224:225], v[224:225], 1.0 op_sel_hi:[1,0]
	v_pk_add_f32 v[190:191], v[190:191], 1.0 op_sel_hi:[1,0]
	v_rcp_f32_e32 v224, v224
	v_rcp_f32_e32 v225, v225
	v_rcp_f32_e32 v190, v190
	v_rcp_f32_e32 v191, v191
	v_pk_mul_f32 v[220:221], v[220:221], v[224:225]
	v_pk_mul_f32 v[222:223], v[222:223], v[190:191]
	v_cvt_pk_bf16_f32 v204, v220, v221
	v_cvt_pk_bf16_f32 v205, v222, v223
	v_add_u32_e32 v243, 0x42000, v237
	global_store_dwordx4 v243, v[202:205], s[24:25]
	v_pk_mul_f32 v[28:29], v[28:29], v[234:235] op_sel_hi:[1,0]
	v_pk_mul_f32 v[30:31], v[30:31], v[234:235] op_sel_hi:[1,0]
	v_pk_mul_f32 v[24:25], v[24:25], v[234:235] op_sel_hi:[1,0]
	v_pk_mul_f32 v[26:27], v[26:27], v[234:235] op_sel_hi:[1,0]
	v_pk_fma_f32 v[220:221], v[108:109], v[28:29], v[100:101]
	v_pk_fma_f32 v[222:223], v[110:111], v[30:31], v[102:103]
	v_pk_fma_f32 v[248:249], v[104:105], v[24:25], v[96:97]
	v_pk_fma_f32 v[250:251], v[106:107], v[26:27], v[98:99]
	v_fmac_f32_dpp v220, v28, v116 row_shr:1 row_mask:0xf bank_mask:0xf
	v_fmac_f32_dpp v221, v29, v117 row_shr:1 row_mask:0xf bank_mask:0xf
	v_fmac_f32_dpp v222, v30, v118 row_shr:1 row_mask:0xf bank_mask:0xf
	v_fmac_f32_dpp v223, v31, v119 row_shr:1 row_mask:0xf bank_mask:0xf
	v_fmac_f32_dpp v248, v24, v112 row_shr:1 row_mask:0xf bank_mask:0xf
	v_fmac_f32_dpp v249, v25, v113 row_shr:1 row_mask:0xf bank_mask:0xf
	v_fmac_f32_dpp v250, v26, v114 row_shr:1 row_mask:0xf bank_mask:0xf
	v_fmac_f32_dpp v251, v27, v115 row_shr:1 row_mask:0xf bank_mask:0xf
	v_fmac_f32_dpp v220, v84, v116 row_shl:15 row_mask:0xf bank_mask:0xf
	v_fmac_f32_dpp v221, v85, v117 row_shl:15 row_mask:0xf bank_mask:0xf
	v_fmac_f32_dpp v222, v86, v118 row_shl:15 row_mask:0xf bank_mask:0xf
	v_fmac_f32_dpp v223, v87, v119 row_shl:15 row_mask:0xf bank_mask:0xf
	v_fmac_f32_dpp v248, v80, v112 row_shl:15 row_mask:0xf bank_mask:0xf
	v_fmac_f32_dpp v249, v81, v113 row_shl:15 row_mask:0xf bank_mask:0xf
	v_fmac_f32_dpp v250, v82, v114 row_shl:15 row_mask:0xf bank_mask:0xf
	v_fmac_f32_dpp v251, v83, v115 row_shl:15 row_mask:0xf bank_mask:0xf
	v_fmac_f32_dpp v220, v28, v124 row_shr:2 row_mask:0xf bank_mask:0xf
	v_fmac_f32_dpp v221, v29, v125 row_shr:2 row_mask:0xf bank_mask:0xf
	v_fmac_f32_dpp v222, v30, v126 row_shr:2 row_mask:0xf bank_mask:0xf
	v_fmac_f32_dpp v223, v31, v127 row_shr:2 row_mask:0xf bank_mask:0xf
	v_fmac_f32_dpp v248, v24, v120 row_shr:2 row_mask:0xf bank_mask:0xf
	v_fmac_f32_dpp v249, v25, v121 row_shr:2 row_mask:0xf bank_mask:0xf
	v_fmac_f32_dpp v250, v26, v122 row_shr:2 row_mask:0xf bank_mask:0xf
	v_fmac_f32_dpp v251, v27, v123 row_shr:2 row_mask:0xf bank_mask:0xf
	v_fmac_f32_dpp v220, v84, v124 row_shl:14 row_mask:0xf bank_mask:0xf
	v_fmac_f32_dpp v221, v85, v125 row_shl:14 row_mask:0xf bank_mask:0xf
	v_fmac_f32_dpp v222, v86, v126 row_shl:14 row_mask:0xf bank_mask:0xf
	v_fmac_f32_dpp v223, v87, v127 row_shl:14 row_mask:0xf bank_mask:0xf
	v_fmac_f32_dpp v248, v80, v120 row_shl:14 row_mask:0xf bank_mask:0xf
	v_fmac_f32_dpp v249, v81, v121 row_shl:14 row_mask:0xf bank_mask:0xf
	v_fmac_f32_dpp v250, v82, v122 row_shl:14 row_mask:0xf bank_mask:0xf
	v_fmac_f32_dpp v251, v83, v123 row_shl:14 row_mask:0xf bank_mask:0xf
	v_pk_mul_f32 v[224:225], v[220:221], s[100:101] op_sel_hi:[1,0]
	v_pk_mul_f32 v[190:191], v[222:223], s[100:101] op_sel_hi:[1,0]
	v_exp_f32_e32 v224, v224
	v_exp_f32_e32 v225, v225
	v_exp_f32_e32 v190, v190
	v_exp_f32_e32 v191, v191
	v_pk_mul_f32 v[220:221], v[220:221], v[248:249]
	v_pk_mul_f32 v[222:223], v[222:223], v[250:251]
; __device__ __forceinline__ unsigned cvt_pk_bf16(float lo, float hi) { unsigned r; asm volatile("v_cvt_pk_bf16_f32 %0, %1, %2" : "=v"(r) : "v"(lo), "v"(hi)); return r; }
; __device__ __forceinline__ float dpp_ror1(float x) { return __int_as_float(__builtin_amdgcn_update_dpp(0, __float_as_int(x), 0x121, 0xf, 0xf, false)); }
; __device__ __forceinline__ float dpp_ror2(float x) { return __int_as_float(__builtin_amdgcn_update_dpp(0, __float_as_int(x), 0x122, 0xf, 0xf, false)); }
;     __device__ __forceinline__ void operator()(const f32x4 (&acc)[2][2][4][2], const Unit& u, int wr, int wc, int fr, int fq) const {
;     ...
;                 for (int m = 0; m < 4; ++m) {
;                     f32x4 cur[2], h[2];
; #pragma unroll
;                     for (int bj = 0; bj < 2; ++bj) { cur[bj] = acc[ai][bj][m][n] * rs[ai][m]; f32x4 x1, x2;
; #pragma unroll
;                         for (int e = 0; e < 4; ++e) { const float c1 = dpp_ror1(cur[bj][e]), p1 = dpp_ror1(pg[bj][e]), c2 = dpp_ror2(cur[bj][e]), p2 = dpp_ror2(pg[bj][e]);
;                             x1[e] = fr >= 1 ? c1 : p1; x2[e] = fr >= 2 ? c2 : p2; }
;                         h[bj] = bb[bj] + w0[bj] * x2 + w1[bj] * x1 + w2[bj] * cur[bj]; }
;                     if (ai == 0 && wr == 0 && m == 0 && fr < 2) {
;                         *(f32x4*)(hc0 + (size_t)(u.pm * 2 + fr) * FF2 + gcol + 4 * n) = h[0]; *(f32x4*)(hc0 + (size_t)(u.pm * 2 + fr) * FF2 + FF + gcol + 4 * n) = h[1]; }
;                     f32x4 a;
; #pragma unroll
;                     for (int e = 0; e < 4; ++e) { const float g = h[0][e]; a[e] = g * __builtin_amdgcn_rcpf(1.0f + __builtin_amdgcn_exp2f(-1.4426950408889634f * g)) * h[1][e]; }
;                     const unsigned p0 = cvt_pk_bf16(a[0], a[1]), p1 = cvt_pk_bf16(a[2], a[3]);
;                     if (n == 0) { pk_lo[ai][m][0] = p0; pk_lo[ai][m][1] = p1; }
;                     else { u32x4 w; w.x = pk_lo[ai][m][0]; w.y = pk_lo[ai][m][1]; w.z = p0; w.w = p1;
;                         *(u32x4*)(act + (size_t)(u.pm * BM + ai * HALF + wr * 64 + m * 16 + fr) * FF + gcol) = w; }
;                     pg[0] = cur[0]; pg[1] = cur[1];
	v_pk_add_f32 v[224:225], v[224:225], 1.0 op_sel_hi:[1,0]
	v_pk_add_f32 v[190:191], v[190:191], 1.0 op_sel_hi:[1,0]
	v_rcp_f32_e32 v224, v224
	v_rcp_f32_e32 v225, v225
	v_rcp_f32_e32 v190, v190
	v_rcp_f32_e32 v191, v191
	v_pk_mul_f32 v[220:221], v[220:221], v[224:225]
	v_pk_mul_f32 v[222:223], v[222:223], v[190:191]
	v_cvt_pk_bf16_f32 v162, v220, v221
	v_cvt_pk_bf16_f32 v163, v222, v223
	v_add_u32_e32 v243, 0xb0000, v237
	global_store_dwordx4 v243, v[160:163], s[24:25]
	v_pk_mul_f32 v[20:21], v[20:21], v[236:237] op_sel_hi:[1,0]
	v_pk_mul_f32 v[22:23], v[22:23], v[236:237] op_sel_hi:[1,0]
	v_pk_mul_f32 v[16:17], v[16:17], v[236:237] op_sel_hi:[1,0]
	v_pk_mul_f32 v[18:19], v[18:19], v[236:237] op_sel_hi:[1,0]
	v_pk_fma_f32 v[220:221], v[108:109], v[20:21], v[100:101]
	v_pk_fma_f32 v[222:223], v[110:111], v[22:23], v[102:103]
	v_pk_fma_f32 v[248:249], v[104:105], v[16:17], v[96:97]
	v_pk_fma_f32 v[250:251], v[106:107], v[18:19], v[98:99]
	v_fmac_f32_dpp v220, v20, v116 row_shr:1 row_mask:0xf bank_mask:0xf
	v_fmac_f32_dpp v221, v21, v117 row_shr:1 row_mask:0xf bank_mask:0xf
	v_fmac_f32_dpp v222, v22, v118 row_shr:1 row_mask:0xf bank_mask:0xf
	v_fmac_f32_dpp v223, v23, v119 row_shr:1 row_mask:0xf bank_mask:0xf
	v_fmac_f32_dpp v248, v16, v112 row_shr:1 row_mask:0xf bank_mask:0xf
	v_fmac_f32_dpp v249, v17, v113 row_shr:1 row_mask:0xf bank_mask:0xf
	v_fmac_f32_dpp v250, v18, v114 row_shr:1 row_mask:0xf bank_mask:0xf
	v_fmac_f32_dpp v251, v19, v115 row_shr:1 row_mask:0xf bank_mask:0xf
	v_fmac_f32_dpp v220, v28, v116 row_shl:15 row_mask:0xf bank_mask:0xf
	v_fmac_f32_dpp v221, v29, v117 row_shl:15 row_mask:0xf bank_mask:0xf
	v_fmac_f32_dpp v222, v30, v118 row_shl:15 row_mask:0xf bank_mask:0xf
	v_fmac_f32_dpp v223, v31, v119 row_shl:15 row_mask:0xf bank_mask:0xf
	v_fmac_f32_dpp v248, v24, v112 row_shl:15 row_mask:0xf bank_mask:0xf
	v_fmac_f32_dpp v249, v25, v113 row_shl:15 row_mask:0xf bank_mask:0xf
	v_fmac_f32_dpp v250, v26, v114 row_shl:15 row_mask:0xf bank_mask:0xf
	v_fmac_f32_dpp v251, v27, v115 row_shl:15 row_mask:0xf bank_mask:0xf
	v_fmac_f32_dpp v220, v20, v124 row_shr:2 row_mask:0xf bank_mask:0xf
	v_fmac_f32_dpp v221, v21, v125 row_shr:2 row_mask:0xf bank_mask:0xf
	v_fmac_f32_dpp v222, v22, v126 row_shr:2 row_mask:0xf bank_mask:0xf
	v_fmac_f32_dpp v223, v23, v127 row_shr:2 row_mask:0xf bank_mask:0xf
	v_fmac_f32_dpp v248, v16, v120 row_shr:2 row_mask:0xf bank_mask:0xf
	v_fmac_f32_dpp v249, v17, v121 row_shr:2 row_mask:0xf bank_mask:0xf
	v_fmac_f32_dpp v250, v18, v122 row_shr:2 row_mask:0xf bank_mask:0xf
	v_fmac_f32_dpp v251, v19, v123 row_shr:2 row_mask:0xf bank_mask:0xf
	v_fmac_f32_dpp v220, v28, v124 row_shl:14 row_mask:0xf bank_mask:0xf
	v_fmac_f32_dpp v221, v29, v125 row_shl:14 row_mask:0xf bank_mask:0xf
	v_fmac_f32_dpp v222, v30, v126 row_shl:14 row_mask:0xf bank_mask:0xf
	v_fmac_f32_dpp v223, v31, v127 row_shl:14 row_mask:0xf bank_mask:0xf
	v_fmac_f32_dpp v248, v24, v120 row_shl:14 row_mask:0xf bank_mask:0xf
	v_fmac_f32_dpp v249, v25, v121 row_shl:14 row_mask:0xf bank_mask:0xf
	v_fmac_f32_dpp v250, v26, v122 row_shl:14 row_mask:0xf bank_mask:0xf
	v_fmac_f32_dpp v251, v27, v123 row_shl:14 row_mask:0xf bank_mask:0xf
	v_pk_mul_f32 v[224:225], v[220:221], s[100:101] op_sel_hi:[1,0]
	v_pk_mul_f32 v[190:191], v[222:223], s[100:101] op_sel_hi:[1,0]
	v_exp_f32_e32 v224, v224
	v_exp_f32_e32 v225, v225
	v_exp_f32_e32 v190, v190
	v_exp_f32_e32 v191, v191
	v_pk_mul_f32 v[220:221], v[220:221], v[248:249]
	v_pk_mul_f32 v[222:223], v[222:223], v[250:251]
	v_pk_add_f32 v[224:225], v[224:225], 1.0 op_sel_hi:[1,0]
	v_pk_add_f32 v[190:191], v[190:191], 1.0 op_sel_hi:[1,0]
	v_rcp_f32_e32 v224, v224
	v_rcp_f32_e32 v225, v225
	v_rcp_f32_e32 v190, v190
	v_rcp_f32_e32 v191, v191
	v_pk_mul_f32 v[220:221], v[220:221], v[224:225]
	v_pk_mul_f32 v[222:223], v[222:223], v[190:191]
	v_cvt_pk_bf16_f32 v166, v220, v221
	v_cvt_pk_bf16_f32 v167, v222, v223
	v_add_u32_e32 v243, 0xc6000, v237
	global_store_dwordx4 v243, v[164:167], s[24:25]
	v_pk_mul_f32 v[12:13], v[12:13], v[238:239] op_sel_hi:[1,0]
	v_pk_mul_f32 v[14:15], v[14:15], v[238:239] op_sel_hi:[1,0]
	v_pk_mul_f32 v[8:9], v[8:9], v[238:239] op_sel_hi:[1,0]
	v_pk_mul_f32 v[10:11], v[10:11], v[238:239] op_sel_hi:[1,0]
	v_pk_fma_f32 v[220:221], v[108:109], v[12:13], v[100:101]
	v_pk_fma_f32 v[222:223], v[110:111], v[14:15], v[102:103]
	v_pk_fma_f32 v[248:249], v[104:105], v[8:9], v[96:97]
	v_pk_fma_f32 v[250:251], v[106:107], v[10:11], v[98:99]
	v_fmac_f32_dpp v220, v12, v116 row_shr:1 row_mask:0xf bank_mask:0xf
	v_fmac_f32_dpp v221, v13, v117 row_shr:1 row_mask:0xf bank_mask:0xf
	v_fmac_f32_dpp v222, v14, v118 row_shr:1 row_mask:0xf bank_mask:0xf
	v_fmac_f32_dpp v223, v15, v119 row_shr:1 row_mask:0xf bank_mask:0xf
	v_fmac_f32_dpp v248, v8, v112 row_shr:1 row_mask:0xf bank_mask:0xf
	v_fmac_f32_dpp v249, v9, v113 row_shr:1 row_mask:0xf bank_mask:0xf
	v_fmac_f32_dpp v250, v10, v114 row_shr:1 row_mask:0xf bank_mask:0xf
	v_fmac_f32_dpp v251, v11, v115 row_shr:1 row_mask:0xf bank_mask:0xf
	v_fmac_f32_dpp v220, v20, v116 row_shl:15 row_mask:0xf bank_mask:0xf
	v_fmac_f32_dpp v221, v21, v117 row_shl:15 row_mask:0xf bank_mask:0xf
	v_fmac_f32_dpp v222, v22, v118 row_shl:15 row_mask:0xf bank_mask:0xf
	v_fmac_f32_dpp v223, v23, v119 row_shl:15 row_mask:0xf bank_mask:0xf
	v_fmac_f32_dpp v248, v16, v112 row_shl:15 row_mask:0xf bank_mask:0xf
	v_fmac_f32_dpp v249, v17, v113 row_shl:15 row_mask:0xf bank_mask:0xf
	v_fmac_f32_dpp v250, v18, v114 row_shl:15 row_mask:0xf bank_mask:0xf
	v_fmac_f32_dpp v251, v19, v115 row_shl:15 row_mask:0xf bank_mask:0xf
	v_fmac_f32_dpp v220, v12, v124 row_shr:2 row_mask:0xf bank_mask:0xf
; #define PG8_LAS __attribute__((address_space(3)))
; __device__ __forceinline__ unsigned cvt_pk_bf16(float lo, float hi) { unsigned r; asm volatile("v_cvt_pk_bf16_f32 %0, %1, %2" : "=v"(r) : "v"(lo), "v"(hi)); return r; }
; __device__ __forceinline__ float dpp_ror1(float x) { return __int_as_float(__builtin_amdgcn_update_dpp(0, __float_as_int(x), 0x121, 0xf, 0xf, false)); }
;     __device__ __forceinline__ void operator()(const f32x4 (&acc)[2][2][4][2], const Unit& u, int wr, int wc, int fr, int fq) const {
;     ...
;                     for (int n = 0; n < 2; ++n) { const f32x4 x = acc[ai][bj][3][n] * rs[ai][3];
;                         *(PG8_LAS f32x4*)(halo + ((ai * 2 + wr) * 2 + (fr - 14)) * 256 + bj * HALF + lcol + 4 * n) = x;
;                         if (ai == 1 && wr == 1) *(f32x4*)(rawh + (size_t)(u.pm * 2 + (fr - 14)) * FF2 + bj * FF + gcol + 4 * n) = x; }
;     ...
;                 for (int m = 0; m < 4; ++m) {
;                     f32x4 cur[2], h[2];
; #pragma unroll
;                     for (int bj = 0; bj < 2; ++bj) { cur[bj] = acc[ai][bj][m][n] * rs[ai][m]; f32x4 x1, x2;
; #pragma unroll
;                         for (int e = 0; e < 4; ++e) { const float c1 = dpp_ror1(cur[bj][e]), p1 = dpp_ror1(pg[bj][e]), c2 = dpp_ror2(cur[bj][e]), p2 = dpp_ror2(pg[bj][e]);
;                             x1[e] = fr >= 1 ? c1 : p1; x2[e] = fr >= 2 ? c2 : p2; }
;                         h[bj] = bb[bj] + w0[bj] * x2 + w1[bj] * x1 + w2[bj] * cur[bj]; }
;                     if (ai == 0 && wr == 0 && m == 0 && fr < 2) {
;                         *(f32x4*)(hc0 + (size_t)(u.pm * 2 + fr) * FF2 + gcol + 4 * n) = h[0]; *(f32x4*)(hc0 + (size_t)(u.pm * 2 + fr) * FF2 + FF + gcol + 4 * n) = h[1]; }
;                     f32x4 a;
; #pragma unroll
;                     for (int e = 0; e < 4; ++e) { const float g = h[0][e]; a[e] = g * __builtin_amdgcn_rcpf(1.0f + __builtin_amdgcn_exp2f(-1.4426950408889634f * g)) * h[1][e]; }
;                     const unsigned p0 = cvt_pk_bf16(a[0], a[1]), p1 = cvt_pk_bf16(a[2], a[3]);
;                     if (n == 0) { pk_lo[ai][m][0] = p0; pk_lo[ai][m][1] = p1; }
;                     else { u32x4 w; w.x = pk_lo[ai][m][0]; w.y = pk_lo[ai][m][1]; w.z = p0; w.w = p1;
;                         *(u32x4*)(act + (size_t)(u.pm * BM + ai * HALF + wr * 64 + m * 16 + fr) * FF + gcol) = w; }
	v_fmac_f32_dpp v221, v13, v125 row_shr:2 row_mask:0xf bank_mask:0xf
	v_fmac_f32_dpp v222, v14, v126 row_shr:2 row_mask:0xf bank_mask:0xf
	v_fmac_f32_dpp v223, v15, v127 row_shr:2 row_mask:0xf bank_mask:0xf
	v_fmac_f32_dpp v248, v8, v120 row_shr:2 row_mask:0xf bank_mask:0xf
	v_fmac_f32_dpp v249, v9, v121 row_shr:2 row_mask:0xf bank_mask:0xf
	v_fmac_f32_dpp v250, v10, v122 row_shr:2 row_mask:0xf bank_mask:0xf
	v_fmac_f32_dpp v251, v11, v123 row_shr:2 row_mask:0xf bank_mask:0xf
	v_fmac_f32_dpp v220, v20, v124 row_shl:14 row_mask:0xf bank_mask:0xf
	v_fmac_f32_dpp v221, v21, v125 row_shl:14 row_mask:0xf bank_mask:0xf
	v_fmac_f32_dpp v222, v22, v126 row_shl:14 row_mask:0xf bank_mask:0xf
	v_fmac_f32_dpp v223, v23, v127 row_shl:14 row_mask:0xf bank_mask:0xf
	v_fmac_f32_dpp v248, v16, v120 row_shl:14 row_mask:0xf bank_mask:0xf
	v_fmac_f32_dpp v249, v17, v121 row_shl:14 row_mask:0xf bank_mask:0xf
	v_fmac_f32_dpp v250, v18, v122 row_shl:14 row_mask:0xf bank_mask:0xf
	v_fmac_f32_dpp v251, v19, v123 row_shl:14 row_mask:0xf bank_mask:0xf
	v_pk_mul_f32 v[224:225], v[220:221], s[100:101] op_sel_hi:[1,0]
	v_pk_mul_f32 v[190:191], v[222:223], s[100:101] op_sel_hi:[1,0]
	v_exp_f32_e32 v224, v224
	v_exp_f32_e32 v225, v225
	v_exp_f32_e32 v190, v190
	v_exp_f32_e32 v191, v191
	v_pk_mul_f32 v[220:221], v[220:221], v[248:249]
	v_pk_mul_f32 v[222:223], v[222:223], v[250:251]
	v_pk_add_f32 v[224:225], v[224:225], 1.0 op_sel_hi:[1,0]
	v_pk_add_f32 v[190:191], v[190:191], 1.0 op_sel_hi:[1,0]
	v_rcp_f32_e32 v224, v224
	v_rcp_f32_e32 v225, v225
	v_rcp_f32_e32 v190, v190
	v_rcp_f32_e32 v191, v191
	v_pk_mul_f32 v[220:221], v[220:221], v[224:225]
	v_pk_mul_f32 v[222:223], v[222:223], v[190:191]
	v_cvt_pk_bf16_f32 v180, v220, v221
	v_cvt_pk_bf16_f32 v181, v222, v223
	v_add_u32_e32 v243, 0xdc000, v237
	global_store_dwordx4 v243, v[178:181], s[24:25]
	v_pk_fma_f32 v[220:221], v[108:109], v[4:5], v[100:101]
	v_pk_fma_f32 v[222:223], v[110:111], v[6:7], v[102:103]
	v_pk_fma_f32 v[248:249], v[104:105], v[0:1], v[96:97]
	v_pk_fma_f32 v[250:251], v[106:107], v[2:3], v[98:99]
	v_fmac_f32_dpp v220, v4, v116 row_shr:1 row_mask:0xf bank_mask:0xf
	v_fmac_f32_dpp v221, v5, v117 row_shr:1 row_mask:0xf bank_mask:0xf
	v_fmac_f32_dpp v222, v6, v118 row_shr:1 row_mask:0xf bank_mask:0xf
	v_fmac_f32_dpp v223, v7, v119 row_shr:1 row_mask:0xf bank_mask:0xf
	v_fmac_f32_dpp v248, v0, v112 row_shr:1 row_mask:0xf bank_mask:0xf
	v_fmac_f32_dpp v249, v1, v113 row_shr:1 row_mask:0xf bank_mask:0xf
	v_fmac_f32_dpp v250, v2, v114 row_shr:1 row_mask:0xf bank_mask:0xf
	v_fmac_f32_dpp v251, v3, v115 row_shr:1 row_mask:0xf bank_mask:0xf
	v_fmac_f32_dpp v220, v12, v116 row_shl:15 row_mask:0xf bank_mask:0xf
	v_fmac_f32_dpp v221, v13, v117 row_shl:15 row_mask:0xf bank_mask:0xf
	v_fmac_f32_dpp v222, v14, v118 row_shl:15 row_mask:0xf bank_mask:0xf
	v_fmac_f32_dpp v223, v15, v119 row_shl:15 row_mask:0xf bank_mask:0xf
	v_fmac_f32_dpp v248, v8, v112 row_shl:15 row_mask:0xf bank_mask:0xf
	v_fmac_f32_dpp v249, v9, v113 row_shl:15 row_mask:0xf bank_mask:0xf
	v_fmac_f32_dpp v250, v10, v114 row_shl:15 row_mask:0xf bank_mask:0xf
	v_fmac_f32_dpp v251, v11, v115 row_shl:15 row_mask:0xf bank_mask:0xf
	v_fmac_f32_dpp v220, v4, v124 row_shr:2 row_mask:0xf bank_mask:0xf
	v_fmac_f32_dpp v221, v5, v125 row_shr:2 row_mask:0xf bank_mask:0xf
	v_fmac_f32_dpp v222, v6, v126 row_shr:2 row_mask:0xf bank_mask:0xf
	v_fmac_f32_dpp v223, v7, v127 row_shr:2 row_mask:0xf bank_mask:0xf
	v_fmac_f32_dpp v248, v0, v120 row_shr:2 row_mask:0xf bank_mask:0xf
	v_fmac_f32_dpp v249, v1, v121 row_shr:2 row_mask:0xf bank_mask:0xf
	v_fmac_f32_dpp v250, v2, v122 row_shr:2 row_mask:0xf bank_mask:0xf
	v_fmac_f32_dpp v251, v3, v123 row_shr:2 row_mask:0xf bank_mask:0xf
	v_fmac_f32_dpp v220, v12, v124 row_shl:14 row_mask:0xf bank_mask:0xf
	v_fmac_f32_dpp v221, v13, v125 row_shl:14 row_mask:0xf bank_mask:0xf
	v_fmac_f32_dpp v222, v14, v126 row_shl:14 row_mask:0xf bank_mask:0xf
	v_fmac_f32_dpp v223, v15, v127 row_shl:14 row_mask:0xf bank_mask:0xf
	v_fmac_f32_dpp v248, v8, v120 row_shl:14 row_mask:0xf bank_mask:0xf
	v_fmac_f32_dpp v249, v9, v121 row_shl:14 row_mask:0xf bank_mask:0xf
	v_fmac_f32_dpp v250, v10, v122 row_shl:14 row_mask:0xf bank_mask:0xf
	v_fmac_f32_dpp v251, v11, v123 row_shl:14 row_mask:0xf bank_mask:0xf
	v_pk_mul_f32 v[224:225], v[220:221], s[100:101] op_sel_hi:[1,0]
	v_pk_mul_f32 v[190:191], v[222:223], s[100:101] op_sel_hi:[1,0]
	v_exp_f32_e32 v224, v224
	v_exp_f32_e32 v225, v225
	v_exp_f32_e32 v190, v190
	v_exp_f32_e32 v191, v191
	v_pk_mul_f32 v[220:221], v[220:221], v[248:249]
	v_pk_mul_f32 v[222:223], v[222:223], v[250:251]
	v_pk_add_f32 v[224:225], v[224:225], 1.0 op_sel_hi:[1,0]
	v_pk_add_f32 v[190:191], v[190:191], 1.0 op_sel_hi:[1,0]
	v_rcp_f32_e32 v224, v224
	v_rcp_f32_e32 v225, v225
	v_rcp_f32_e32 v190, v190
	v_rcp_f32_e32 v191, v191
	v_pk_mul_f32 v[220:221], v[220:221], v[224:225]
	v_pk_mul_f32 v[222:223], v[222:223], v[190:191]
	v_cvt_pk_bf16_f32 v184, v220, v221
	v_cvt_pk_bf16_f32 v185, v222, v223
	v_add_u32_e32 v243, 0xf2000, v237
	global_store_dwordx4 v243, v[182:185], s[24:25]
	s_and_b64 vcc, exec, s[20:21]
	s_cbranch_vccnz .Lp7_norawh
	s_mov_b64 s[0:1], exec
	s_andn2_b64 exec, exec, s[40:41]
	v_add_u32_e32 v227, s11, v210
	v_mad_u32_u24 v227, v227, s70, v231
	v_add_u32_e32 v229, 0x2c00, v227
	global_store_dwordx4 v227, v[68:71], s[18:19]
	global_store_dwordx4 v227, v[4:7], s[18:19] offset:16
	global_store_dwordx4 v229, v[64:67], s[18:19]
	global_store_dwordx4 v229, v[0:3], s[18:19] offset:16
	s_mov_b64 exec, s[0:1]
.Lp7_norawh:
	s_andn2_b64 vcc, exec, s[46:47]
	s_mov_b64 s[0:1], -1
	s_cbranch_vccnz .LBB0_893
	v_readlane_b32 s0, v255, 44
	v_readlane_b32 s1, v255, 45
	s_andn2_b64 vcc, exec, s[0:1]
	s_cbranch_vccnz .LBB0_892
	s_barrier
	s_branch .LBB0_892

; #define LAS __attribute__((address_space(3)))
; __global__ void __launch_bounds__(512, 2) fwd_megakernel(Args a) {
;     extern __shared__ __attribute__((aligned(16))) unsigned char lds_raw[];
;     LAS unsigned char* lds = (LAS unsigned char*)lds_raw;
	.amdhsa_kernel _Z14fwd_megakernel4Args
		.amdhsa_group_segment_fixed_size 256
		.amdhsa_private_segment_fixed_size 0
		.amdhsa_kernarg_size 448
		.amdhsa_user_sgpr_count 2
		.amdhsa_user_sgpr_dispatch_ptr 0
		.amdhsa_user_sgpr_queue_ptr 0
		.amdhsa_user_sgpr_kernarg_segment_ptr 1
		.amdhsa_user_sgpr_dispatch_id 0
		.amdhsa_user_sgpr_kernarg_preload_length 0
		.amdhsa_user_sgpr_kernarg_preload_offset 0
		.amdhsa_user_sgpr_private_segment_size 0
		.amdhsa_uses_dynamic_stack 0
		.amdhsa_enable_private_segment 0
		.amdhsa_system_sgpr_workgroup_id_x 1
		.amdhsa_system_sgpr_workgroup_id_y 0
		.amdhsa_system_sgpr_workgroup_id_z 0
		.amdhsa_system_sgpr_workgroup_info 0
		.amdhsa_system_vgpr_workitem_id 2
		.amdhsa_next_free_vgpr 256
		.amdhsa_next_free_sgpr 102
		.amdhsa_accum_offset 256
		.amdhsa_reserve_vcc 1
		.amdhsa_float_round_mode_32 0
		.amdhsa_float_round_mode_16_64 0
		.amdhsa_float_denorm_mode_32 3
		.amdhsa_float_denorm_mode_16_64 3
		.amdhsa_dx10_clamp 1
		.amdhsa_ieee_mode 1
		.amdhsa_fp16_overflow 0
		.amdhsa_tg_split 0
		.amdhsa_exception_fp_ieee_invalid_op 0
		.amdhsa_exception_fp_denorm_src 0
		.amdhsa_exception_fp_ieee_div_zero 0
		.amdhsa_exception_fp_ieee_overflow 0
		.amdhsa_exception_fp_ieee_underflow 0
		.amdhsa_exception_fp_ieee_inexact 0
		.amdhsa_exception_int_div_zero 0
	.end_amdhsa_kernel

amdhsa.kernels:
  - .agpr_count:     0
    .args:
      - .offset:         0
        .size:           192
        .value_kind:     by_value
      - .offset:         192
        .size:           4
        .value_kind:     hidden_block_count_x
      - .offset:         196
        .size:           4
        .value_kind:     hidden_block_count_y
      - .offset:         200
        .size:           4
        .value_kind:     hidden_block_count_z
      - .offset:         204
        .size:           2
        .value_kind:     hidden_group_size_x
      - .offset:         206
        .size:           2
        .value_kind:     hidden_group_size_y
      - .offset:         208
        .size:           2
        .value_kind:     hidden_group_size_z
      - .offset:         210
        .size:           2
        .value_kind:     hidden_remainder_x
      - .offset:         212
        .size:           2
        .value_kind:     hidden_remainder_y
      - .offset:         214
        .size:           2
        .value_kind:     hidden_remainder_z
      - .offset:         232
        .size:           8
        .value_kind:     hidden_global_offset_x
      - .offset:         240
        .size:           8
        .value_kind:     hidden_global_offset_y
      - .offset:         248
        .size:           8
        .value_kind:     hidden_global_offset_z
      - .offset:         256
        .size:           2
        .value_kind:     hidden_grid_dims
      - .offset:         280
        .size:           8
        .value_kind:     hidden_multigrid_sync_arg
      - .offset:         312
        .size:           4
        .value_kind:     hidden_dynamic_lds_size
    .group_segment_fixed_size: 256
    .kernarg_segment_align: 8
    .kernarg_segment_size: 448
    .language:       OpenCL C
    .language_version:
      - 2
      - 0
    .max_flat_workgroup_size: 512
    .name:           _Z14fwd_megakernel4Args
    .private_segment_fixed_size: 0
    .sgpr_count:     108
    .sgpr_spill_count: 180
    .symbol:         _Z14fwd_megakernel4Args.kd
    .uniform_work_group_size: 1
    .uses_dynamic_stack: false
    .vgpr_count:     256
    .vgpr_spill_count: 0
    .wavefront_size: 64
